# E28a: softmax scale folded into q before fp6 rounding (q*8C, MFMA block scale 2^-3 on the Q operand); MLA loop constants C=1; same dtypes
# speedup vs baseline: 1.1268x; 1.0064x over previous
; DEVINL float bflo(unsigned u) { return __uint_as_float(u << 16); }
; DEVINL float bfhi(unsigned u) { return __uint_as_float(u & 0xffff0000u); }
; DEVINL void qr_row(const Params& p, bf16_t* rowp, int posi) {
;   float f[64];
; #pragma unroll
;   for (int c = 0; c < 8; ++c) { const u32x4 w = *reinterpret_cast<const u32x4*>(rowp + c * 8);
; #pragma unroll
;     for (int j = 0; j < 4; ++j) { f[c * 8 + 2 * j] = bflo(w[j]); f[c * 8 + 2 * j + 1] = bfhi(w[j]); } }
;   float ss = 0.f;
; #pragma unroll
;   for (int d = 0; d < 64; ++d) ss += f[d] * f[d];
;   const float r = rsqrtf(ss * (1.f / 64.f) + EPS);
;   const float pos = (float)posi;
;   f32x16 a0, b0, a1, b1;
; #pragma unroll
;   for (int i = 0; i < 32; ++i) {
;     const float x1 = f[i] * r * p.qpe_w[i], x2 = f[i + 32] * r * p.qpe_w[i + 32];
.LBB0_478:
	v_or_b32_e32 v132, s29, v134
	v_ashrrev_i32_e32 v133, 31, v132
	v_lshlrev_b64 v[132:133], 21, v[132:133]
	v_lshl_add_u64 v[132:133], v[130:131], 0, v[132:133]
	global_load_dwordx4 v[0:3], v129, s[54:55] offset:48
	global_load_dwordx4 v[4:7], v129, s[54:55] offset:32
	global_load_dwordx4 v[8:11], v129, s[54:55] offset:16
	global_load_dwordx4 v[16:19], v129, s[54:55]
	global_load_dwordx4 v[12:15], v129, s[54:55] offset:176
	global_load_dwordx4 v[20:23], v129, s[54:55] offset:160
	global_load_dwordx4 v[24:27], v129, s[54:55] offset:144
	global_load_dwordx4 v[28:31], v129, s[54:55] offset:128
	global_load_dwordx4 v[32:35], v129, s[54:55] offset:112
	global_load_dwordx4 v[36:39], v129, s[54:55] offset:96
	global_load_dwordx4 v[40:43], v129, s[54:55] offset:80
	global_load_dwordx4 v[48:51], v129, s[54:55] offset:64
	global_load_dwordx4 v[44:47], v129, s[54:55] offset:240
	global_load_dwordx4 v[52:55], v129, s[54:55] offset:224
	global_load_dwordx4 v[56:59], v129, s[54:55] offset:208
	global_load_dwordx4 v[60:63], v129, s[54:55] offset:192
	flat_load_dwordx4 v[136:139], v[132:133]
	flat_load_dwordx4 v[140:143], v[132:133] offset:64
	flat_load_dwordx4 v[144:147], v[132:133] offset:16
	flat_load_dwordx4 v[148:151], v[132:133] offset:80
	flat_load_dwordx4 v[152:155], v[132:133] offset:32
	flat_load_dwordx4 v[156:159], v[132:133] offset:96
	flat_load_dwordx4 v[160:163], v[132:133] offset:48
	flat_load_dwordx4 v[164:167], v[132:133] offset:112
	s_mov_b32 s29, 1
	s_and_b64 vcc, exec, s[34:35]
	s_mov_b64 s[34:35], 0
	s_waitcnt vmcnt(0) lgkmcnt(0)
	v_lshlrev_b32_e32 v168, 16, v136
	v_and_b32_e32 v169, 0xffff0000, v136
	v_lshlrev_b32_e32 v136, 16, v137
	v_and_b32_e32 v137, 0xffff0000, v137
	v_pk_mul_f32 v[200:201], v[168:169], v[168:169]
	v_pk_mul_f32 v[204:205], v[136:137], v[136:137]
	v_add_f32_e32 v128, v200, v201
	v_lshlrev_b32_e32 v172, 16, v138
	v_and_b32_e32 v173, 0xffff0000, v138
	v_add_f32_e32 v128, v204, v128
	v_pk_mul_f32 v[208:209], v[172:173], v[172:173]
	v_add_f32_e32 v128, v205, v128
	v_lshlrev_b32_e32 v138, 16, v139
	v_and_b32_e32 v139, 0xffff0000, v139
	v_add_f32_e32 v128, v208, v128
	v_pk_mul_f32 v[212:213], v[138:139], v[138:139]
	v_add_f32_e32 v128, v209, v128
	v_lshlrev_b32_e32 v176, 16, v144
	v_and_b32_e32 v177, 0xffff0000, v144
	v_add_f32_e32 v128, v212, v128
	v_pk_mul_f32 v[216:217], v[176:177], v[176:177]
	v_add_f32_e32 v128, v213, v128
	v_lshlrev_b32_e32 v144, 16, v145
	v_and_b32_e32 v145, 0xffff0000, v145
	v_add_f32_e32 v128, v216, v128
	v_pk_mul_f32 v[220:221], v[144:145], v[144:145]
	v_add_f32_e32 v128, v217, v128
	v_lshlrev_b32_e32 v180, 16, v146
	v_and_b32_e32 v181, 0xffff0000, v146
	v_add_f32_e32 v128, v220, v128
	v_pk_mul_f32 v[230:231], v[180:181], v[180:181]
	v_add_f32_e32 v128, v221, v128
	v_lshlrev_b32_e32 v146, 16, v147
	v_and_b32_e32 v147, 0xffff0000, v147
	v_add_f32_e32 v128, v230, v128
	v_pk_mul_f32 v[234:235], v[146:147], v[146:147]
	v_add_f32_e32 v128, v231, v128
	v_lshlrev_b32_e32 v184, 16, v152
	v_and_b32_e32 v185, 0xffff0000, v152
	v_add_f32_e32 v128, v234, v128
	v_pk_mul_f32 v[238:239], v[184:185], v[184:185]
	v_add_f32_e32 v128, v235, v128
	v_lshlrev_b32_e32 v152, 16, v153
	v_and_b32_e32 v153, 0xffff0000, v153
	v_add_f32_e32 v128, v238, v128
	v_pk_mul_f32 v[242:243], v[152:153], v[152:153]
	v_add_f32_e32 v128, v239, v128
	v_lshlrev_b32_e32 v188, 16, v154
	v_and_b32_e32 v189, 0xffff0000, v154
	v_add_f32_e32 v128, v242, v128
	v_pk_mul_f32 v[246:247], v[188:189], v[188:189]
	v_add_f32_e32 v128, v243, v128
	v_lshlrev_b32_e32 v154, 16, v155
	v_and_b32_e32 v155, 0xffff0000, v155
	v_add_f32_e32 v128, v246, v128
	v_pk_mul_f32 v[200:201], v[154:155], v[154:155]
	v_add_f32_e32 v128, v247, v128
	v_lshlrev_b32_e32 v192, 16, v160
	v_and_b32_e32 v193, 0xffff0000, v160
	v_add_f32_e32 v128, v200, v128
	v_pk_mul_f32 v[208:209], v[192:193], v[192:193]
	v_add_f32_e32 v128, v201, v128
	v_lshlrev_b32_e32 v160, 16, v161
	v_and_b32_e32 v161, 0xffff0000, v161
	v_add_f32_e32 v128, v208, v128
	v_pk_mul_f32 v[216:217], v[160:161], v[160:161]
	v_add_f32_e32 v128, v209, v128
	v_lshlrev_b32_e32 v196, 16, v162
	v_and_b32_e32 v197, 0xffff0000, v162
	v_add_f32_e32 v128, v216, v128
	v_pk_mul_f32 v[230:231], v[196:197], v[196:197]
	v_add_f32_e32 v128, v217, v128
	v_lshlrev_b32_e32 v162, 16, v163
	v_and_b32_e32 v163, 0xffff0000, v163
	v_add_f32_e32 v128, v230, v128
	v_pk_mul_f32 v[238:239], v[162:163], v[162:163]
	v_add_f32_e32 v128, v231, v128
	v_lshlrev_b32_e32 v170, 16, v140
	v_and_b32_e32 v171, 0xffff0000, v140
	v_add_f32_e32 v128, v238, v128
	v_pk_mul_f32 v[202:203], v[170:171], v[170:171]
	v_add_f32_e32 v128, v239, v128
	v_lshlrev_b32_e32 v140, 16, v141
	v_and_b32_e32 v141, 0xffff0000, v141
	v_add_f32_e32 v128, v202, v128
	v_pk_mul_f32 v[206:207], v[140:141], v[140:141]
	v_add_f32_e32 v128, v203, v128
	v_lshlrev_b32_e32 v174, 16, v142
	v_and_b32_e32 v175, 0xffff0000, v142
	v_add_f32_e32 v128, v206, v128
	v_pk_mul_f32 v[210:211], v[174:175], v[174:175]
	v_add_f32_e32 v128, v207, v128
	v_lshlrev_b32_e32 v142, 16, v143
	v_and_b32_e32 v143, 0xffff0000, v143
	v_add_f32_e32 v128, v210, v128
	v_pk_mul_f32 v[214:215], v[142:143], v[142:143]
	v_add_f32_e32 v128, v211, v128
	v_lshlrev_b32_e32 v178, 16, v148
	v_and_b32_e32 v179, 0xffff0000, v148
	v_add_f32_e32 v128, v214, v128
	v_pk_mul_f32 v[218:219], v[178:179], v[178:179]
	v_add_f32_e32 v128, v215, v128
	v_lshlrev_b32_e32 v148, 16, v149
	v_and_b32_e32 v149, 0xffff0000, v149
	v_add_f32_e32 v128, v218, v128
	v_pk_mul_f32 v[222:223], v[148:149], v[148:149]
	v_add_f32_e32 v128, v219, v128
	v_lshlrev_b32_e32 v182, 16, v150
	v_and_b32_e32 v183, 0xffff0000, v150
	v_add_f32_e32 v128, v222, v128
; DEVINL void qr_row(const Params& p, bf16_t* rowp, int posi) {
;     ...
;   float ss = 0.f;
; #pragma unroll
;   for (int d = 0; d < 64; ++d) ss += f[d] * f[d];
;   const float r = rsqrtf(ss * (1.f / 64.f) + EPS);
;   const float pos = (float)posi;
;   f32x16 a0, b0, a1, b1;
; #pragma unroll
;   for (int i = 0; i < 32; ++i) {
;     const float x1 = f[i] * r * p.qpe_w[i], x2 = f[i + 32] * r * p.qpe_w[i + 32];
;     const float invf = exp2f(-(float)i * (13.287712379549449f / 32.f));
;     const float ang = pos * invf;
;     const float k = rintf(ang * 0.15915494309189535f);
;     float rr = fmaf(-k, 6.2831855f, ang); rr = fmaf(-k, -1.7484555e-7f, rr);
;     const float c = __cosf(rr), s = __sinf(rr);
;     const float y1 = x1 * c - x2 * s, y2 = x2 * c + x1 * s;
	v_pk_mul_f32 v[232:233], v[182:183], v[182:183]
	v_add_f32_e32 v128, v223, v128
	v_lshlrev_b32_e32 v150, 16, v151
	v_and_b32_e32 v151, 0xffff0000, v151
	v_add_f32_e32 v128, v232, v128
	v_pk_mul_f32 v[236:237], v[150:151], v[150:151]
	v_add_f32_e32 v128, v233, v128
	v_lshlrev_b32_e32 v186, 16, v156
	v_and_b32_e32 v187, 0xffff0000, v156
	v_add_f32_e32 v128, v236, v128
	v_pk_mul_f32 v[240:241], v[186:187], v[186:187]
	v_add_f32_e32 v128, v237, v128
	v_lshlrev_b32_e32 v156, 16, v157
	v_and_b32_e32 v157, 0xffff0000, v157
	v_add_f32_e32 v128, v240, v128
	v_pk_mul_f32 v[244:245], v[156:157], v[156:157]
	v_add_f32_e32 v128, v241, v128
	v_lshlrev_b32_e32 v190, 16, v158
	v_and_b32_e32 v191, 0xffff0000, v158
	v_add_f32_e32 v128, v244, v128
	v_pk_mul_f32 v[248:249], v[190:191], v[190:191]
	v_add_f32_e32 v128, v245, v128
	v_lshlrev_b32_e32 v158, 16, v159
	v_and_b32_e32 v159, 0xffff0000, v159
	v_add_f32_e32 v128, v248, v128
	v_pk_mul_f32 v[204:205], v[158:159], v[158:159]
	v_add_f32_e32 v128, v249, v128
	v_lshlrev_b32_e32 v194, 16, v164
	v_and_b32_e32 v195, 0xffff0000, v164
	v_add_f32_e32 v128, v204, v128
	v_pk_mul_f32 v[212:213], v[194:195], v[194:195]
	v_add_f32_e32 v128, v205, v128
	v_lshlrev_b32_e32 v164, 16, v165
	v_and_b32_e32 v165, 0xffff0000, v165
	v_add_f32_e32 v128, v212, v128
	v_pk_mul_f32 v[220:221], v[164:165], v[164:165]
	v_add_f32_e32 v128, v213, v128
	v_lshlrev_b32_e32 v198, 16, v166
	v_and_b32_e32 v199, 0xffff0000, v166
	v_add_f32_e32 v128, v220, v128
	v_pk_mul_f32 v[234:235], v[198:199], v[198:199]
	v_add_f32_e32 v128, v221, v128
	v_lshlrev_b32_e32 v166, 16, v167
	v_and_b32_e32 v167, 0xffff0000, v167
	v_add_f32_e32 v128, v234, v128
	v_pk_mul_f32 v[242:243], v[166:167], v[166:167]
	v_add_f32_e32 v128, v235, v128
	v_add_f32_e32 v128, v242, v128
	v_add_f32_e32 v128, v243, v128
	v_fmamk_f32 v128, v128, 0x3c800000, v227
	v_mul_f32_e32 v135, 0x4b800000, v128
	v_cmp_gt_f32_e64 s[4:5], s46, v128
	s_nop 1
	v_cndmask_b32_e64 v128, v128, v135, s[4:5]
	v_rsq_f32_e32 v128, v128
	s_nop 0
	v_mul_f32_e32 v135, 0x45800000, v128
	v_cndmask_b32_e64 v128, v128, v135, s[4:5]
	v_mul_f32_e32 v128, 0x3f553b94, v128
	v_pk_mul_f32 v[186:187], v[128:129], v[186:187] op_sel_hi:[0,1]
	v_pk_mul_f32 v[152:153], v[128:129], v[152:153] op_sel_hi:[0,1]
	v_pk_mul_f32 v[156:157], v[128:129], v[156:157] op_sel_hi:[0,1]
	v_pk_mul_f32 v[190:191], v[128:129], v[190:191] op_sel_hi:[0,1]
	v_pk_mul_f32 v[158:159], v[128:129], v[158:159] op_sel_hi:[0,1]
	v_pk_mul_f32 v[194:195], v[128:129], v[194:195] op_sel_hi:[0,1]
	v_pk_mul_f32 v[164:165], v[128:129], v[164:165] op_sel_hi:[0,1]
	v_pk_mul_f32 v[198:199], v[128:129], v[198:199] op_sel_hi:[0,1]
	v_pk_mul_f32 v[166:167], v[128:129], v[166:167] op_sel_hi:[0,1]
	v_pk_mul_f32 v[168:169], v[128:129], v[168:169] op_sel_hi:[0,1]
	v_pk_mul_f32 v[170:171], v[128:129], v[170:171] op_sel_hi:[0,1]
	v_pk_mul_f32 v[136:137], v[128:129], v[136:137] op_sel_hi:[0,1]
	v_pk_mul_f32 v[140:141], v[128:129], v[140:141] op_sel_hi:[0,1]
	v_pk_mul_f32 v[172:173], v[128:129], v[172:173] op_sel_hi:[0,1]
	v_pk_mul_f32 v[174:175], v[128:129], v[174:175] op_sel_hi:[0,1]
	v_pk_mul_f32 v[138:139], v[128:129], v[138:139] op_sel_hi:[0,1]
	v_pk_mul_f32 v[142:143], v[128:129], v[142:143] op_sel_hi:[0,1]
	v_pk_mul_f32 v[176:177], v[128:129], v[176:177] op_sel_hi:[0,1]
	v_pk_mul_f32 v[178:179], v[128:129], v[178:179] op_sel_hi:[0,1]
	v_pk_mul_f32 v[144:145], v[128:129], v[144:145] op_sel_hi:[0,1]
	v_pk_mul_f32 v[148:149], v[128:129], v[148:149] op_sel_hi:[0,1]
	v_pk_mul_f32 v[180:181], v[128:129], v[180:181] op_sel_hi:[0,1]
	v_pk_mul_f32 v[182:183], v[128:129], v[182:183] op_sel_hi:[0,1]
	v_pk_mul_f32 v[146:147], v[128:129], v[146:147] op_sel_hi:[0,1]
	v_pk_mul_f32 v[150:151], v[128:129], v[150:151] op_sel_hi:[0,1]
	v_pk_mul_f32 v[184:185], v[128:129], v[184:185] op_sel_hi:[0,1]
	v_pk_mul_f32 v[188:189], v[128:129], v[188:189] op_sel_hi:[0,1]
	v_pk_mul_f32 v[154:155], v[128:129], v[154:155] op_sel_hi:[0,1]
	v_pk_mul_f32 v[192:193], v[128:129], v[192:193] op_sel_hi:[0,1]
	v_pk_mul_f32 v[160:161], v[128:129], v[160:161] op_sel_hi:[0,1]
	v_pk_mul_f32 v[196:197], v[128:129], v[196:197] op_sel_hi:[0,1]
	v_pk_mul_f32 v[162:163], v[128:129], v[162:163] op_sel_hi:[0,1]
	v_pk_mul_f32 v[60:61], v[60:61], v[186:187]
	v_pk_mul_f32 v[50:51], v[50:51], v[152:153]
	v_pk_mul_f32 v[62:63], v[62:63], v[156:157]
	v_pk_mul_f32 v[56:57], v[56:57], v[190:191]
	v_pk_mul_f32 v[58:59], v[58:59], v[158:159]
	v_pk_mul_f32 v[52:53], v[52:53], v[194:195]
	v_pk_mul_f32 v[54:55], v[54:55], v[164:165]
	v_pk_mul_f32 v[44:45], v[44:45], v[198:199]
	v_pk_mul_f32 v[46:47], v[46:47], v[166:167]
	v_pk_mul_f32 v[152:153], v[16:17], v[168:169]
	v_pk_mul_f32 v[16:17], v[28:29], v[170:171]
	v_pk_mul_f32 v[136:137], v[18:19], v[136:137]
	v_pk_mul_f32 v[18:19], v[30:31], v[140:141]
	v_pk_mul_f32 v[140:141], v[8:9], v[172:173]
; DEVINL i32x6 pk6(const f32x16& a, const f32x16& b) { return __builtin_amdgcn_cvt_scalef32_2xpk16_fp6_f32(a, b, 1.0f); }
; DEVINL void qr_row(const Params& p, bf16_t* rowp, int posi) {
;     ...
;   for (int i = 0; i < 32; ++i) {
;     const float x1 = f[i] * r * p.qpe_w[i], x2 = f[i + 32] * r * p.qpe_w[i + 32];
;     const float invf = exp2f(-(float)i * (13.287712379549449f / 32.f));
;     const float ang = pos * invf;
;     const float k = rintf(ang * 0.15915494309189535f);
;     float rr = fmaf(-k, 6.2831855f, ang); rr = fmaf(-k, -1.7484555e-7f, rr);
;     const float c = __cosf(rr), s = __sinf(rr);
;     const float y1 = x1 * c - x2 * s, y2 = x2 * c + x1 * s;
;     if (i < 16) { a0[i] = y1; a1[i] = y2; } else { b0[i - 16] = y1; b1[i - 16] = y2; }
;   }
;   const i32x6 w0 = pk6(a0, b0), w1 = pk6(a1, b1);
;   u32x2* d = reinterpret_cast<u32x2*>(rowp);
;   d[0] = u32x2{(unsigned)w0[0], (unsigned)w0[1]}; d[1] = u32x2{(unsigned)w0[2], (unsigned)w0[3]}; d[2] = u32x2{(unsigned)w0[4], (unsigned)w0[5]};
;   d[3] = u32x2{(unsigned)w1[0], (unsigned)w1[1]}; d[4] = u32x2{(unsigned)w1[2], (unsigned)w1[3]}; d[5] = u32x2{(unsigned)w1[4], (unsigned)w1[5]};
	v_pk_mul_f32 v[8:9], v[24:25], v[174:175]
	v_pk_mul_f32 v[138:139], v[10:11], v[138:139]
	v_pk_mul_f32 v[10:11], v[26:27], v[142:143]
	v_pk_mul_f32 v[142:143], v[4:5], v[176:177]
	v_pk_mul_f32 v[4:5], v[20:21], v[178:179]
	v_pk_mul_f32 v[144:145], v[6:7], v[144:145]
	v_pk_mul_f32 v[6:7], v[22:23], v[148:149]
	v_pk_mul_f32 v[148:149], v[0:1], v[180:181]
	v_pk_mul_f32 v[0:1], v[12:13], v[182:183]
	v_pk_mul_f32 v[146:147], v[2:3], v[146:147]
	v_pk_mul_f32 v[2:3], v[14:15], v[150:151]
	v_pk_mul_f32 v[48:49], v[48:49], v[184:185]
	v_pk_mul_f32 v[40:41], v[40:41], v[188:189]
	v_pk_mul_f32 v[42:43], v[42:43], v[154:155]
	v_pk_mul_f32 v[36:37], v[36:37], v[192:193]
	v_pk_mul_f32 v[38:39], v[38:39], v[160:161]
	v_pk_mul_f32 v[32:33], v[32:33], v[196:197]
	v_pk_mul_f32 v[34:35], v[34:35], v[162:163]
	v_pk_mul_f32 v[12:13], v[66:67], v[60:61]
	v_pk_mul_f32 v[14:15], v[70:71], v[62:63]
	v_pk_mul_f32 v[20:21], v[74:75], v[56:57]
	v_pk_mul_f32 v[22:23], v[78:79], v[58:59]
	v_pk_mul_f32 v[24:25], v[82:83], v[52:53]
	v_pk_mul_f32 v[26:27], v[86:87], v[54:55]
	v_pk_mul_f32 v[28:29], v[90:91], v[44:45]
	v_pk_mul_f32 v[30:31], v[94:95], v[46:47]
	v_pk_mul_f32 v[60:61], v[64:65], v[60:61]
	v_pk_mul_f32 v[62:63], v[68:69], v[62:63]
	v_pk_mul_f32 v[56:57], v[72:73], v[56:57]
	v_pk_mul_f32 v[58:59], v[76:77], v[58:59]
	v_pk_mul_f32 v[52:53], v[80:81], v[52:53]
	v_pk_mul_f32 v[54:55], v[84:85], v[54:55]
	v_pk_mul_f32 v[44:45], v[88:89], v[44:45]
	v_pk_mul_f32 v[46:47], v[92:93], v[46:47]
	v_pk_mul_f32 v[150:151], v[98:99], v[16:17]
	v_pk_mul_f32 v[154:155], v[102:103], v[18:19]
	v_pk_mul_f32 v[156:157], v[106:107], v[8:9]
	v_pk_mul_f32 v[158:159], v[110:111], v[10:11]
	v_pk_mul_f32 v[160:161], v[114:115], v[4:5]
	v_pk_mul_f32 v[162:163], v[118:119], v[6:7]
	v_pk_mul_f32 v[164:165], v[122:123], v[0:1]
	v_pk_mul_f32 v[166:167], v[126:127], v[2:3]
	v_pk_mul_f32 v[168:169], v[96:97], v[16:17]
	v_pk_mul_f32 v[170:171], v[100:101], v[18:19]
	v_pk_mul_f32 v[172:173], v[104:105], v[8:9]
	v_pk_mul_f32 v[174:175], v[108:109], v[10:11]
	v_pk_mul_f32 v[176:177], v[112:113], v[4:5]
	v_pk_mul_f32 v[178:179], v[116:117], v[6:7]
	v_pk_mul_f32 v[180:181], v[120:121], v[0:1]
	v_pk_mul_f32 v[182:183], v[124:125], v[2:3]
	v_pk_fma_f32 v[0:1], v[64:65], v[48:49], v[12:13]
	v_pk_fma_f32 v[2:3], v[68:69], v[50:51], v[14:15]
	v_pk_fma_f32 v[4:5], v[72:73], v[40:41], v[20:21]
	v_pk_fma_f32 v[6:7], v[76:77], v[42:43], v[22:23]
	v_pk_fma_f32 v[8:9], v[80:81], v[36:37], v[24:25]
	v_pk_fma_f32 v[10:11], v[84:85], v[38:39], v[26:27]
	v_pk_fma_f32 v[12:13], v[88:89], v[32:33], v[28:29]
	v_pk_fma_f32 v[14:15], v[92:93], v[34:35], v[30:31]
	v_pk_fma_f32 v[16:17], v[66:67], v[48:49], v[60:61] neg_lo:[0,0,1] neg_hi:[0,0,1]
	v_pk_fma_f32 v[18:19], v[70:71], v[50:51], v[62:63] neg_lo:[0,0,1] neg_hi:[0,0,1]
	v_pk_fma_f32 v[20:21], v[74:75], v[40:41], v[56:57] neg_lo:[0,0,1] neg_hi:[0,0,1]
	v_pk_fma_f32 v[22:23], v[78:79], v[42:43], v[58:59] neg_lo:[0,0,1] neg_hi:[0,0,1]
	v_pk_fma_f32 v[24:25], v[82:83], v[36:37], v[52:53] neg_lo:[0,0,1] neg_hi:[0,0,1]
	v_pk_fma_f32 v[26:27], v[86:87], v[38:39], v[54:55] neg_lo:[0,0,1] neg_hi:[0,0,1]
	v_pk_fma_f32 v[28:29], v[90:91], v[32:33], v[44:45] neg_lo:[0,0,1] neg_hi:[0,0,1]
	v_pk_fma_f32 v[30:31], v[94:95], v[34:35], v[46:47] neg_lo:[0,0,1] neg_hi:[0,0,1]
	v_pk_fma_f32 v[32:33], v[96:97], v[152:153], v[150:151]
	v_pk_fma_f32 v[34:35], v[100:101], v[136:137], v[154:155]
	v_pk_fma_f32 v[36:37], v[104:105], v[140:141], v[156:157]
	v_pk_fma_f32 v[38:39], v[108:109], v[138:139], v[158:159]
	v_pk_fma_f32 v[40:41], v[112:113], v[142:143], v[160:161]
	v_pk_fma_f32 v[42:43], v[116:117], v[144:145], v[162:163]
	v_pk_fma_f32 v[44:45], v[120:121], v[148:149], v[164:165]
	v_pk_fma_f32 v[46:47], v[124:125], v[146:147], v[166:167]
	v_pk_fma_f32 v[48:49], v[98:99], v[152:153], v[168:169] neg_lo:[0,0,1] neg_hi:[0,0,1]
	v_pk_fma_f32 v[50:51], v[102:103], v[136:137], v[170:171] neg_lo:[0,0,1] neg_hi:[0,0,1]
	v_pk_fma_f32 v[52:53], v[106:107], v[140:141], v[172:173] neg_lo:[0,0,1] neg_hi:[0,0,1]
	v_pk_fma_f32 v[54:55], v[110:111], v[138:139], v[174:175] neg_lo:[0,0,1] neg_hi:[0,0,1]
	v_pk_fma_f32 v[56:57], v[114:115], v[142:143], v[176:177] neg_lo:[0,0,1] neg_hi:[0,0,1]
	v_pk_fma_f32 v[58:59], v[118:119], v[144:145], v[178:179] neg_lo:[0,0,1] neg_hi:[0,0,1]
	v_pk_fma_f32 v[60:61], v[122:123], v[148:149], v[180:181] neg_lo:[0,0,1] neg_hi:[0,0,1]
	v_pk_fma_f32 v[62:63], v[126:127], v[146:147], v[182:183] neg_lo:[0,0,1] neg_hi:[0,0,1]
	v_cvt_scalef32_2xpk16_fp6_f32 v[0:5], v[32:47], v[0:15], 1.0
	v_cvt_scalef32_2xpk16_fp6_f32 v[16:21], v[48:63], v[16:31], 1.0
	flat_store_dwordx4 v[132:133], v[16:19]
	v_mov_b32_e32 v6, v20
	v_mov_b32_e32 v7, v21
	v_mov_b32_e32 v8, v0
	v_mov_b32_e32 v9, v1
	flat_store_dwordx4 v[132:133], v[2:5] offset:32
	flat_store_dwordx4 v[132:133], v[6:9] offset:16
	s_cbranch_vccnz .LBB0_478
	s_mov_b64 s[4:5], 0

; DEVINL unsigned cvtpk(float lo, float hi) { unsigned r; asm("v_cvt_pk_bf16_f32 %0, %1, %2" : "=v"(r) : "v"(lo), "v"(hi)); return r; }
; DEVINL void phase_gemm2(const Params& p, char* lds) {
;     ...
;       gemm_tile<true>(p, A, A, 1 << 30, 512, WuqT + (size_t)pn * 256 * QR, QR, QR / BK, lds, [=](int row, int col, f32x4 v) {
;         const float s = rs[row];
;         u32x2 w = {cvtpk(v[0] * s, v[1] * s), cvtpk(v[2] * s, v[3] * s)};
;         const int n = pn * 256 + col, h = n >> 7, d = n & 127;
;         *reinterpret_cast<u32x2*>(QN + ((size_t)h * SEQ + grow0 + row) * 128 + d) = w;
;       });
;       asm volatile("s_waitcnt vmcnt(0)" ::: "memory"); __syncthreads();
.LBB0_485:
	s_or_b64 exec, exec, s[4:5]
	s_lshl_b32 s4, s28, 1
	s_ashr_i32 s5, s4, 31
	s_lshl_b64 s[34:35], s[4:5], 22
	s_add_u32 s34, s12, s34
	v_lshl_or_b32 v130, v130, 6, v131
	s_addc_u32 s35, s13, s35
	s_add_i32 s5, 0, 0x20000
	v_lshl_add_u32 v133, v130, 2, s5
	ds_read_b32 v138, v133
	v_lshrrev_b32_e32 v128, 6, v128
	v_ashrrev_i32_e32 v131, 31, v130
	v_lshl_add_u64 v[134:135], v[130:131], 0, s[16:17]
	v_lshlrev_b64 v[134:135], 8, v[134:135]
	s_waitcnt lgkmcnt(0)
	v_mul_f32_e32 v124, v124, v138
	v_mul_f32_e32 v125, v125, v138
	v_cvt_pk_bf16_f32 v124, v124, v125
	v_mul_f32_e32 v125, v126, v138
	v_mul_f32_e32 v126, v127, v138
	v_cvt_pk_bf16_f32 v125, v125, v126
	v_lshlrev_b32_e32 v126, 6, v128
	v_and_b32_e32 v126, 0xc0, v126
	v_lshl_add_u64 v[136:137], s[34:35], 0, v[134:135]
	v_lshl_or_b32 v128, v132, 3, v126
	v_lshl_add_u64 v[126:127], v[136:137], 0, v[128:129]
	flat_store_dwordx2 v[126:127], v[124:125]
	ds_read_b32 v124, v133
	s_or_b32 s38, s4, 1
	s_ashr_i32 s39, s38, 31
	s_lshl_b64 s[38:39], s[38:39], 22
	s_add_u32 s38, s12, s38
	s_waitcnt lgkmcnt(0)
	v_mul_f32_e32 v120, v120, v124
	v_mul_f32_e32 v121, v121, v124
	v_cvt_pk_bf16_f32 v120, v120, v121
	v_mul_f32_e32 v121, v122, v124
	v_mul_f32_e32 v122, v123, v124
	v_cvt_pk_bf16_f32 v121, v121, v122
	flat_store_dwordx2 v[126:127], v[120:121] offset:32
	v_or_b32_e32 v120, 16, v130
	v_lshl_add_u32 v124, v120, 2, s5
	ds_read_b32 v125, v124
	v_ashrrev_i32_e32 v121, 31, v120
	v_lshl_add_u64 v[120:121], v[120:121], 0, s[16:17]
	v_lshlrev_b64 v[120:121], 8, v[120:121]
	v_lshl_add_u64 v[122:123], s[34:35], 0, v[120:121]
	s_waitcnt lgkmcnt(0)
	v_mul_f32_e32 v116, v116, v125
	v_mul_f32_e32 v117, v117, v125
	v_cvt_pk_bf16_f32 v116, v116, v117
	v_mul_f32_e32 v117, v118, v125
	v_mul_f32_e32 v118, v119, v125
	v_cvt_pk_bf16_f32 v117, v117, v118
	v_lshl_add_u64 v[118:119], v[122:123], 0, v[128:129]
	flat_store_dwordx2 v[118:119], v[116:117]
	ds_read_b32 v116, v124
	s_addc_u32 s39, s13, s39
	s_waitcnt lgkmcnt(0)
	v_mul_f32_e32 v112, v112, v116
	v_mul_f32_e32 v113, v113, v116
	v_cvt_pk_bf16_f32 v112, v112, v113
	v_mul_f32_e32 v113, v114, v116
	v_mul_f32_e32 v114, v115, v116
	v_cvt_pk_bf16_f32 v113, v113, v114
	flat_store_dwordx2 v[118:119], v[112:113] offset:32
	v_or_b32_e32 v112, 32, v130
	v_lshl_add_u32 v116, v112, 2, s5
	ds_read_b32 v117, v116
	v_ashrrev_i32_e32 v113, 31, v112
	v_lshl_add_u64 v[112:113], v[112:113], 0, s[16:17]
	v_lshlrev_b64 v[112:113], 8, v[112:113]
	v_lshl_add_u64 v[114:115], s[34:35], 0, v[112:113]
	s_waitcnt lgkmcnt(0)
	v_mul_f32_e32 v108, v108, v117
	v_mul_f32_e32 v109, v109, v117
	v_cvt_pk_bf16_f32 v108, v108, v109
	v_mul_f32_e32 v109, v110, v117
	v_mul_f32_e32 v110, v111, v117
	v_cvt_pk_bf16_f32 v109, v109, v110
	v_lshl_add_u64 v[110:111], v[114:115], 0, v[128:129]
	flat_store_dwordx2 v[110:111], v[108:109]
	ds_read_b32 v108, v116
	s_waitcnt lgkmcnt(0)
	v_mul_f32_e32 v104, v104, v108
	v_mul_f32_e32 v105, v105, v108
	v_cvt_pk_bf16_f32 v104, v104, v105
	v_mul_f32_e32 v105, v106, v108
	v_mul_f32_e32 v106, v107, v108
	v_cvt_pk_bf16_f32 v105, v105, v106
	flat_store_dwordx2 v[110:111], v[104:105] offset:32
	v_or_b32_e32 v104, 48, v130
	v_lshl_add_u32 v108, v104, 2, s5
	ds_read_b32 v109, v108
	v_ashrrev_i32_e32 v105, 31, v104
	v_lshl_add_u64 v[104:105], v[104:105], 0, s[16:17]
	v_lshlrev_b64 v[104:105], 8, v[104:105]
	v_lshl_add_u64 v[106:107], s[34:35], 0, v[104:105]
	s_waitcnt lgkmcnt(0)
	v_mul_f32_e32 v100, v100, v109
	v_mul_f32_e32 v101, v101, v109
	v_cvt_pk_bf16_f32 v100, v100, v101
	v_mul_f32_e32 v101, v102, v109
	v_mul_f32_e32 v102, v103, v109
	v_cvt_pk_bf16_f32 v101, v101, v102
	v_lshl_add_u64 v[102:103], v[106:107], 0, v[128:129]
	flat_store_dwordx2 v[102:103], v[100:101]
	ds_read_b32 v100, v108
	s_waitcnt lgkmcnt(0)
	v_mul_f32_e32 v96, v96, v100
	v_mul_f32_e32 v97, v97, v100
	v_cvt_pk_bf16_f32 v96, v96, v97
	v_mul_f32_e32 v97, v98, v100
	v_mul_f32_e32 v98, v99, v100
	v_cvt_pk_bf16_f32 v97, v97, v98
	flat_store_dwordx2 v[102:103], v[96:97] offset:32
	ds_read_b32 v98, v133
	v_lshl_add_u64 v[96:97], s[38:39], 0, v[134:135]
	s_waitcnt lgkmcnt(0)
	v_mul_f32_e32 v92, v92, v98
	v_mul_f32_e32 v93, v93, v98
	v_cvt_pk_bf16_f32 v92, v92, v93
	v_mul_f32_e32 v93, v94, v98
	v_mul_f32_e32 v94, v95, v98
	v_cvt_pk_bf16_f32 v93, v93, v94
	v_lshl_add_u64 v[94:95], v[96:97], 0, v[128:129]
	flat_store_dwordx2 v[94:95], v[92:93]
	ds_read_b32 v92, v133
	s_waitcnt lgkmcnt(0)
	v_mul_f32_e32 v88, v88, v92
	v_mul_f32_e32 v89, v89, v92
	v_cvt_pk_bf16_f32 v88, v88, v89
	v_mul_f32_e32 v89, v90, v92
	v_mul_f32_e32 v90, v91, v92
	v_cvt_pk_bf16_f32 v89, v89, v90
	flat_store_dwordx2 v[94:95], v[88:89] offset:32
	ds_read_b32 v90, v124
	v_lshl_add_u64 v[88:89], s[38:39], 0, v[120:121]
	s_waitcnt lgkmcnt(0)
	v_mul_f32_e32 v84, v84, v90
	v_mul_f32_e32 v85, v85, v90
	v_cvt_pk_bf16_f32 v84, v84, v85
	v_mul_f32_e32 v85, v86, v90
	v_mul_f32_e32 v86, v87, v90
	v_cvt_pk_bf16_f32 v85, v85, v86
	v_lshl_add_u64 v[86:87], v[88:89], 0, v[128:129]
	flat_store_dwordx2 v[86:87], v[84:85]
	ds_read_b32 v84, v124
	s_waitcnt lgkmcnt(0)
	v_mul_f32_e32 v80, v80, v84
	v_mul_f32_e32 v81, v81, v84
	v_cvt_pk_bf16_f32 v80, v80, v81
	v_mul_f32_e32 v81, v82, v84
	v_mul_f32_e32 v82, v83, v84
	v_cvt_pk_bf16_f32 v81, v81, v82
	flat_store_dwordx2 v[86:87], v[80:81] offset:32
	ds_read_b32 v82, v116
	v_lshl_add_u64 v[80:81], s[38:39], 0, v[112:113]
	s_waitcnt lgkmcnt(0)
	v_mul_f32_e32 v76, v76, v82
	v_mul_f32_e32 v77, v77, v82
	v_cvt_pk_bf16_f32 v76, v76, v77
	v_mul_f32_e32 v77, v78, v82
	v_mul_f32_e32 v78, v79, v82
	v_cvt_pk_bf16_f32 v77, v77, v78
	v_lshl_add_u64 v[78:79], v[80:81], 0, v[128:129]
	flat_store_dwordx2 v[78:79], v[76:77]
	ds_read_b32 v76, v116
	s_waitcnt lgkmcnt(0)
; DEVINL unsigned cvtpk(float lo, float hi) { unsigned r; asm("v_cvt_pk_bf16_f32 %0, %1, %2" : "=v"(r) : "v"(lo), "v"(hi)); return r; }
; DEVINL void phase_gemm2(const Params& p, char* lds) {
;     ...
;       gemm_tile<true>(p, A, A, 1 << 30, 512, WuqT + (size_t)pn * 256 * QR, QR, QR / BK, lds, [=](int row, int col, f32x4 v) {
;         const float s = rs[row];
;         u32x2 w = {cvtpk(v[0] * s, v[1] * s), cvtpk(v[2] * s, v[3] * s)};
;         const int n = pn * 256 + col, h = n >> 7, d = n & 127;
;         *reinterpret_cast<u32x2*>(QN + ((size_t)h * SEQ + grow0 + row) * 128 + d) = w;
;       });
;       asm volatile("s_waitcnt vmcnt(0)" ::: "memory"); __syncthreads();
	v_mul_f32_e32 v72, v72, v76
	v_mul_f32_e32 v73, v73, v76
	v_cvt_pk_bf16_f32 v72, v72, v73
	v_mul_f32_e32 v73, v74, v76
	v_mul_f32_e32 v74, v75, v76
	v_cvt_pk_bf16_f32 v73, v73, v74
	flat_store_dwordx2 v[78:79], v[72:73] offset:32
	ds_read_b32 v74, v108
	v_lshl_add_u64 v[72:73], s[38:39], 0, v[104:105]
	s_waitcnt lgkmcnt(0)
	v_mul_f32_e32 v68, v68, v74
	v_mul_f32_e32 v69, v69, v74
	v_cvt_pk_bf16_f32 v68, v68, v69
	v_mul_f32_e32 v69, v70, v74
	v_mul_f32_e32 v70, v71, v74
	v_cvt_pk_bf16_f32 v69, v69, v70
	v_lshl_add_u64 v[70:71], v[72:73], 0, v[128:129]
	flat_store_dwordx2 v[70:71], v[68:69]
	ds_read_b32 v68, v108
	s_waitcnt lgkmcnt(0)
	v_mul_f32_e32 v64, v64, v68
	v_mul_f32_e32 v65, v65, v68
	v_cvt_pk_bf16_f32 v64, v64, v65
	v_mul_f32_e32 v65, v66, v68
	v_mul_f32_e32 v66, v67, v68
	v_cvt_pk_bf16_f32 v65, v65, v66
	flat_store_dwordx2 v[70:71], v[64:65] offset:32
	ds_read_b32 v68, v133 offset:512
	v_add_u32_e32 v64, 0x80, v130
	v_ashrrev_i32_e32 v65, 31, v64
	v_lshl_add_u64 v[64:65], v[64:65], 0, s[16:17]
	v_lshlrev_b64 v[64:65], 8, v[64:65]
	s_waitcnt lgkmcnt(0)
	v_mul_f32_e32 v60, v60, v68
	v_mul_f32_e32 v61, v61, v68
	v_lshl_add_u64 v[66:67], s[34:35], 0, v[64:65]
	v_cvt_pk_bf16_f32 v60, v60, v61
	v_mul_f32_e32 v61, v62, v68
	v_mul_f32_e32 v62, v63, v68
	v_cvt_pk_bf16_f32 v61, v61, v62
	v_lshl_add_u64 v[62:63], v[66:67], 0, v[128:129]
	flat_store_dwordx2 v[62:63], v[60:61]
	ds_read_b32 v60, v133 offset:512
	s_waitcnt lgkmcnt(0)
	v_mul_f32_e32 v56, v56, v60
	v_mul_f32_e32 v57, v57, v60
	v_cvt_pk_bf16_f32 v56, v56, v57
	v_mul_f32_e32 v57, v58, v60
	v_mul_f32_e32 v58, v59, v60
	v_cvt_pk_bf16_f32 v57, v57, v58
	flat_store_dwordx2 v[62:63], v[56:57] offset:32
	ds_read_b32 v60, v133 offset:576
	v_add_u32_e32 v56, 0x90, v130
	v_ashrrev_i32_e32 v57, 31, v56
	v_lshl_add_u64 v[56:57], v[56:57], 0, s[16:17]
	v_lshlrev_b64 v[56:57], 8, v[56:57]
	s_waitcnt lgkmcnt(0)
	v_mul_f32_e32 v52, v52, v60
	v_mul_f32_e32 v53, v53, v60
	v_lshl_add_u64 v[58:59], s[34:35], 0, v[56:57]
	v_cvt_pk_bf16_f32 v52, v52, v53
	v_mul_f32_e32 v53, v54, v60
	v_mul_f32_e32 v54, v55, v60
	v_cvt_pk_bf16_f32 v53, v53, v54
	v_lshl_add_u64 v[54:55], v[58:59], 0, v[128:129]
	flat_store_dwordx2 v[54:55], v[52:53]
	ds_read_b32 v52, v133 offset:576
	s_waitcnt lgkmcnt(0)
	v_mul_f32_e32 v48, v48, v52
	v_mul_f32_e32 v49, v49, v52
	v_cvt_pk_bf16_f32 v48, v48, v49
	v_mul_f32_e32 v49, v50, v52
	v_mul_f32_e32 v50, v51, v52
	v_cvt_pk_bf16_f32 v49, v49, v50
	flat_store_dwordx2 v[54:55], v[48:49] offset:32
	ds_read_b32 v52, v133 offset:640
	v_add_u32_e32 v48, 0xa0, v130
	v_ashrrev_i32_e32 v49, 31, v48
	v_lshl_add_u64 v[48:49], v[48:49], 0, s[16:17]
	v_lshlrev_b64 v[48:49], 8, v[48:49]
	s_waitcnt lgkmcnt(0)
	v_mul_f32_e32 v44, v44, v52
	v_mul_f32_e32 v45, v45, v52
	v_lshl_add_u64 v[50:51], s[34:35], 0, v[48:49]
	v_cvt_pk_bf16_f32 v44, v44, v45
	v_mul_f32_e32 v45, v46, v52
	v_mul_f32_e32 v46, v47, v52
	v_cvt_pk_bf16_f32 v45, v45, v46
	v_lshl_add_u64 v[46:47], v[50:51], 0, v[128:129]
	flat_store_dwordx2 v[46:47], v[44:45]
	ds_read_b32 v44, v133 offset:640
	s_waitcnt lgkmcnt(0)
	v_mul_f32_e32 v40, v40, v44
	v_mul_f32_e32 v41, v41, v44
	v_cvt_pk_bf16_f32 v40, v40, v41
	v_mul_f32_e32 v41, v42, v44
	v_mul_f32_e32 v42, v43, v44
	v_cvt_pk_bf16_f32 v41, v41, v42
	flat_store_dwordx2 v[46:47], v[40:41] offset:32
	ds_read_b32 v44, v133 offset:704
	v_add_u32_e32 v40, 0xb0, v130
	v_ashrrev_i32_e32 v41, 31, v40
	v_lshl_add_u64 v[40:41], v[40:41], 0, s[16:17]
	v_lshlrev_b64 v[40:41], 8, v[40:41]
	s_waitcnt lgkmcnt(0)
	v_mul_f32_e32 v36, v36, v44
	v_mul_f32_e32 v37, v37, v44
	v_lshl_add_u64 v[42:43], s[34:35], 0, v[40:41]
	v_cvt_pk_bf16_f32 v36, v36, v37
	v_mul_f32_e32 v37, v38, v44
	v_mul_f32_e32 v38, v39, v44
	v_cvt_pk_bf16_f32 v37, v37, v38
	v_lshl_add_u64 v[38:39], v[42:43], 0, v[128:129]
	flat_store_dwordx2 v[38:39], v[36:37]
	ds_read_b32 v36, v133 offset:704
	s_mov_b64 s[34:35], 0
	s_waitcnt lgkmcnt(0)
	v_mul_f32_e32 v32, v32, v36
	v_mul_f32_e32 v33, v33, v36
	v_cvt_pk_bf16_f32 v32, v32, v33
	v_mul_f32_e32 v33, v34, v36
	v_mul_f32_e32 v34, v35, v36
	v_cvt_pk_bf16_f32 v33, v33, v34
	flat_store_dwordx2 v[38:39], v[32:33] offset:32
	ds_read_b32 v34, v133 offset:512
	v_lshl_add_u64 v[32:33], s[38:39], 0, v[64:65]
	s_waitcnt lgkmcnt(0)
	v_mul_f32_e32 v28, v28, v34
	v_mul_f32_e32 v29, v29, v34
	v_cvt_pk_bf16_f32 v28, v28, v29
	v_mul_f32_e32 v29, v30, v34
	v_mul_f32_e32 v30, v31, v34
	v_cvt_pk_bf16_f32 v29, v29, v30
	v_lshl_add_u64 v[30:31], v[32:33], 0, v[128:129]
	flat_store_dwordx2 v[30:31], v[28:29]
	ds_read_b32 v28, v133 offset:512
	s_waitcnt lgkmcnt(0)
	v_mul_f32_e32 v24, v24, v28
	v_mul_f32_e32 v25, v25, v28
	v_cvt_pk_bf16_f32 v24, v24, v25
	v_mul_f32_e32 v25, v26, v28
	v_mul_f32_e32 v26, v27, v28
	v_cvt_pk_bf16_f32 v25, v25, v26
	flat_store_dwordx2 v[30:31], v[24:25] offset:32
	ds_read_b32 v26, v133 offset:576
	v_lshl_add_u64 v[24:25], s[38:39], 0, v[56:57]
	s_waitcnt lgkmcnt(0)
	v_mul_f32_e32 v20, v20, v26
	v_mul_f32_e32 v21, v21, v26
	v_cvt_pk_bf16_f32 v20, v20, v21
	v_mul_f32_e32 v21, v22, v26
	v_mul_f32_e32 v22, v23, v26
	v_cvt_pk_bf16_f32 v21, v21, v22
	v_lshl_add_u64 v[22:23], v[24:25], 0, v[128:129]
	flat_store_dwordx2 v[22:23], v[20:21]
	ds_read_b32 v20, v133 offset:576
	s_waitcnt lgkmcnt(0)
	v_mul_f32_e32 v16, v16, v20
	v_mul_f32_e32 v17, v17, v20
	v_cvt_pk_bf16_f32 v16, v16, v17
	v_mul_f32_e32 v17, v18, v20
	v_mul_f32_e32 v18, v19, v20
	v_cvt_pk_bf16_f32 v17, v17, v18
	flat_store_dwordx2 v[22:23], v[16:17] offset:32
	ds_read_b32 v18, v133 offset:640
	v_lshl_add_u64 v[16:17], s[38:39], 0, v[48:49]
	s_waitcnt lgkmcnt(0)
	v_mul_f32_e32 v12, v12, v18
	v_mul_f32_e32 v13, v13, v18
	v_cvt_pk_bf16_f32 v12, v12, v13
	v_mul_f32_e32 v13, v14, v18
	v_mul_f32_e32 v14, v15, v18
	v_cvt_pk_bf16_f32 v13, v13, v14
	v_lshl_add_u64 v[14:15], v[16:17], 0, v[128:129]
	flat_store_dwordx2 v[14:15], v[12:13]
	ds_read_b32 v12, v133 offset:640
	s_waitcnt lgkmcnt(0)
	v_mul_f32_e32 v8, v8, v12
	v_mul_f32_e32 v9, v9, v12
	v_cvt_pk_bf16_f32 v8, v8, v9
	v_mul_f32_e32 v9, v10, v12
	v_mul_f32_e32 v10, v11, v12
	v_cvt_pk_bf16_f32 v9, v9, v10
	flat_store_dwordx2 v[14:15], v[8:9] offset:32
	ds_read_b32 v10, v133 offset:704
	v_lshl_add_u64 v[8:9], s[38:39], 0, v[40:41]
	s_waitcnt lgkmcnt(0)
	v_mul_f32_e32 v4, v4, v10
	v_mul_f32_e32 v5, v5, v10
	v_cvt_pk_bf16_f32 v4, v4, v5
	v_mul_f32_e32 v5, v6, v10
	v_mul_f32_e32 v6, v7, v10
	v_cvt_pk_bf16_f32 v5, v5, v6
	v_lshl_add_u64 v[6:7], v[8:9], 0, v[128:129]
	flat_store_dwordx2 v[6:7], v[4:5]
	ds_read_b32 v4, v133 offset:704
	s_waitcnt lgkmcnt(0)
	v_mul_f32_e32 v0, v0, v4
	v_mul_f32_e32 v1, v1, v4
	v_cvt_pk_bf16_f32 v0, v0, v1
	v_mul_f32_e32 v1, v2, v4
	v_mul_f32_e32 v2, v3, v4
	v_cvt_pk_bf16_f32 v1, v1, v2
	flat_store_dwordx2 v[6:7], v[0:1] offset:32
	s_waitcnt vmcnt(0)
	s_waitcnt vmcnt(0) lgkmcnt(0)
	s_barrier
; DEVINL int tidx(const Params& p) { int l; asm volatile("v_mbcnt_lo_u32_b32 %0, -1, 0\n\tv_mbcnt_hi_u32_b32 %0, -1, %0" : "=v"(l)); return p.tid0 + l; }
; DEVINL float bflo(unsigned u) { return __uint_as_float(u << 16); }
; DEVINL float bfhi(unsigned u) { return __uint_as_float(u & 0xffff0000u); }
; DEVINL void qn_row(const Params& p, bf16_t* rowp) {
;   u32x4 raw[16];
; #pragma unroll
;   for (int c = 0; c < 16; ++c) raw[c] = *reinterpret_cast<const u32x4*>(rowp + c * 8);
;   float ss = 0.f;
; #pragma unroll
;   for (int c = 0; c < 16; ++c)
; #pragma unroll
;     for (int j = 0; j < 4; ++j) { const float a = bflo(raw[c][j]), b = bfhi(raw[c][j]); ss += a * a + b * b; }
;   const float r = rsqrtf(ss * (1.f / 128.f) + EPS);
; DEVINL void phase_gemm2(const Params& p, char* lds) {
;     ...
;       { const int tid = tidx(p); qn_row(p, QN + ((size_t)(pn * 2 + (tid >> 8)) * SEQ + grow0 + (tid & 255)) * 128); }
	v_mbcnt_lo_u32_b32 v0, -1, 0
	v_mbcnt_hi_u32_b32 v0, -1, v0
	s_nop 0
	v_add_u32_e32 v2, s3, v0
	v_ashrrev_i32_e32 v0, 8, v2
	v_add_u32_e32 v0, s4, v0
	v_ashrrev_i32_e32 v1, 31, v0
	v_lshlrev_b64 v[0:1], 14, v[0:1]
	v_lshl_add_u64 v[0:1], v[0:1], 0, s[16:17]
	v_and_or_b32 v0, v2, s58, v0
	v_lshlrev_b64 v[0:1], 8, v[0:1]
	v_lshl_add_u64 v[52:53], s[12:13], 0, v[0:1]
	flat_load_dwordx4 v[40:43], v[52:53] offset:224
	flat_load_dwordx4 v[0:3], v[52:53] offset:240
	flat_load_dwordx4 v[4:7], v[52:53] offset:32
	flat_load_dwordx4 v[8:11], v[52:53] offset:48
	flat_load_dwordx4 v[64:67], v[52:53]
	flat_load_dwordx4 v[68:71], v[52:53] offset:16
	flat_load_dwordx4 v[72:75], v[52:53] offset:64
	flat_load_dwordx4 v[76:79], v[52:53] offset:80
	flat_load_dwordx4 v[80:83], v[52:53] offset:96
	flat_load_dwordx4 v[122:125], v[52:53] offset:112
	flat_load_dwordx4 v[48:51], v[52:53] offset:128
	flat_load_dwordx4 v[44:47], v[52:53] offset:144
	flat_load_dwordx4 v[134:137], v[52:53] offset:160
	flat_load_dwordx4 v[146:149], v[52:53] offset:176
	flat_load_dwordx4 v[36:39], v[52:53] offset:192
	flat_load_dwordx4 v[32:35], v[52:53] offset:208
	global_load_dwordx4 v[16:19], v129, s[52:53] offset:64
	global_load_dwordx4 v[20:23], v129, s[52:53] offset:80
	global_load_dwordx4 v[24:27], v129, s[52:53] offset:96
	global_load_dwordx4 v[28:31], v129, s[52:53] offset:112
	s_waitcnt vmcnt(0) lgkmcnt(0)
	v_and_b32_e32 v57, 0xffff0000, v43
	v_and_b32_e32 v59, 0xffff0000, v1
	v_and_b32_e32 v58, 0xffff0000, v0
	v_and_b32_e32 v56, 0xffff0000, v42
	v_lshlrev_b32_e32 v63, 16, v1
	v_lshlrev_b32_e32 v62, 16, v0
	v_pk_mul_f32 v[0:1], v[58:59], v[58:59]
	v_and_b32_e32 v55, 0xffff0000, v3
	v_and_b32_e32 v54, 0xffff0000, v2
	v_lshlrev_b32_e32 v61, 16, v43
	v_lshlrev_b32_e32 v60, 16, v42
	v_pk_mul_f32 v[12:13], v[56:57], v[56:57]
	v_pk_fma_f32 v[120:121], v[62:63], v[62:63], v[0:1]
	v_lshlrev_b32_e32 v43, 16, v3
	v_lshlrev_b32_e32 v42, 16, v2
	v_pk_mul_f32 v[0:1], v[54:55], v[54:55]
	v_pk_fma_f32 v[116:117], v[60:61], v[60:61], v[12:13]
	v_pk_fma_f32 v[126:127], v[42:43], v[42:43], v[0:1]
	v_lshlrev_b32_e32 v84, 16, v4
	v_and_b32_e32 v85, 0xffff0000, v4
	v_lshlrev_b32_e32 v88, 16, v5
	v_and_b32_e32 v89, 0xffff0000, v5
	v_lshlrev_b32_e32 v94, 16, v6
	v_and_b32_e32 v95, 0xffff0000, v6
	v_lshlrev_b32_e32 v100, 16, v7
	v_and_b32_e32 v101, 0xffff0000, v7
	v_lshlrev_b32_e32 v104, 16, v8
	v_and_b32_e32 v105, 0xffff0000, v8
	v_lshlrev_b32_e32 v110, 16, v9
	v_and_b32_e32 v111, 0xffff0000, v9
	v_lshlrev_b32_e32 v112, 16, v10
	v_and_b32_e32 v113, 0xffff0000, v10
	v_lshlrev_b32_e32 v114, 16, v11
	v_and_b32_e32 v115, 0xffff0000, v11
	global_load_dwordx4 v[0:3], v129, s[52:53]
	global_load_dwordx4 v[4:7], v129, s[52:53] offset:16
	global_load_dwordx4 v[8:11], v129, s[52:53] offset:32
	global_load_dwordx4 v[12:15], v129, s[52:53] offset:48
	v_lshlrev_b32_e32 v156, 16, v64
	v_and_b32_e32 v157, 0xffff0000, v64
	v_lshlrev_b32_e32 v158, 16, v65
	v_and_b32_e32 v159, 0xffff0000, v65
	v_lshlrev_b32_e32 v162, 16, v67
	v_and_b32_e32 v163, 0xffff0000, v67
	v_pk_mul_f32 v[204:205], v[156:157], v[156:157]
	v_pk_mul_f32 v[208:209], v[158:159], v[158:159]
	v_lshlrev_b32_e32 v160, 16, v66
	v_and_b32_e32 v161, 0xffff0000, v66
	v_pk_mul_f32 v[230:231], v[162:163], v[162:163]
	v_pk_mul_f32 v[206:207], v[160:161], v[160:161]
	v_add_f32_e32 v128, v230, v231
	v_add_f32_e32 v230, v208, v209
	v_add_f32_e32 v204, v204, v205
	v_lshlrev_b32_e32 v164, 16, v68
	v_and_b32_e32 v165, 0xffff0000, v68
	v_add_f32_e32 v230, v204, v230
	v_add_f32_e32 v206, v206, v207
	v_pk_mul_f32 v[212:213], v[164:165], v[164:165]
	v_lshlrev_b32_e32 v166, 16, v69
	v_and_b32_e32 v167, 0xffff0000, v69
	v_add_f32_e32 v230, v206, v230
	v_pk_mul_f32 v[214:215], v[166:167], v[166:167]
	v_lshlrev_b32_e32 v168, 16, v70
	v_and_b32_e32 v169, 0xffff0000, v70
	v_add_f32_e32 v128, v128, v230
	v_add_f32_e32 v230, v212, v213
	v_pk_mul_f32 v[218:219], v[168:169], v[168:169]
	v_lshlrev_b32_e32 v170, 16, v71
	v_and_b32_e32 v171, 0xffff0000, v71
	v_add_f32_e32 v128, v230, v128
	v_add_f32_e32 v230, v214, v215
	v_pk_mul_f32 v[220:221], v[170:171], v[170:171]
	v_add_f32_e32 v128, v230, v128
	v_add_f32_e32 v230, v218, v219
	v_pk_mul_f32 v[172:173], v[84:85], v[84:85]
	v_add_f32_e32 v128, v230, v128
	v_add_f32_e32 v230, v220, v221
	v_pk_mul_f32 v[174:175], v[88:89], v[88:89]
	v_add_f32_e32 v128, v230, v128
	v_add_f32_e32 v230, v172, v173
	v_pk_mul_f32 v[176:177], v[94:95], v[94:95]
	v_add_f32_e32 v128, v230, v128
	v_add_f32_e32 v230, v174, v175
	v_pk_mul_f32 v[178:179], v[100:101], v[100:101]
	v_add_f32_e32 v128, v230, v128
	v_add_f32_e32 v230, v176, v177
	v_pk_mul_f32 v[180:181], v[104:105], v[104:105]
	v_add_f32_e32 v128, v230, v128
	v_add_f32_e32 v230, v178, v179
	v_pk_mul_f32 v[182:183], v[110:111], v[110:111]
	v_add_f32_e32 v128, v230, v128
	v_add_f32_e32 v230, v180, v181
	v_pk_mul_f32 v[184:185], v[112:113], v[112:113]
	v_add_f32_e32 v128, v230, v128
	v_add_f32_e32 v230, v182, v183
	v_pk_mul_f32 v[186:187], v[114:115], v[114:115]
	v_lshlrev_b32_e32 v138, 16, v72
	v_and_b32_e32 v139, 0xffff0000, v72
	v_add_f32_e32 v128, v230, v128
	v_add_f32_e32 v230, v184, v185
	v_pk_mul_f32 v[232:233], v[138:139], v[138:139]
	v_lshlrev_b32_e32 v130, 16, v73
	v_and_b32_e32 v131, 0xffff0000, v73
	v_add_f32_e32 v128, v230, v128
	v_add_f32_e32 v230, v186, v187
	v_pk_mul_f32 v[234:235], v[130:131], v[130:131]
	v_lshlrev_b32_e32 v132, 16, v74
	v_and_b32_e32 v133, 0xffff0000, v74
	v_add_f32_e32 v128, v230, v128
	v_add_f32_e32 v232, v232, v233
	v_pk_mul_f32 v[236:237], v[132:133], v[132:133]
	v_lshlrev_b32_e32 v140, 16, v75
	v_and_b32_e32 v141, 0xffff0000, v75
	v_add_f32_e32 v128, v232, v128
; DEVINL float bflo(unsigned u) { return __uint_as_float(u << 16); }
; DEVINL float bfhi(unsigned u) { return __uint_as_float(u & 0xffff0000u); }
; DEVINL void qn_row(const Params& p, bf16_t* rowp) {
;     ...
;   float ss = 0.f;
; #pragma unroll
;   for (int c = 0; c < 16; ++c)
; #pragma unroll
;     for (int j = 0; j < 4; ++j) { const float a = bflo(raw[c][j]), b = bfhi(raw[c][j]); ss += a * a + b * b; }
;   const float r = rsqrtf(ss * (1.f / 128.f) + EPS);
	v_add_f32_e32 v234, v234, v235
	v_pk_mul_f32 v[238:239], v[140:141], v[140:141]
	v_lshlrev_b32_e32 v142, 16, v76
	v_and_b32_e32 v143, 0xffff0000, v76
	v_add_f32_e32 v128, v234, v128
	v_add_f32_e32 v236, v236, v237
	v_pk_mul_f32 v[240:241], v[142:143], v[142:143]
	v_lshlrev_b32_e32 v144, 16, v77
	v_and_b32_e32 v145, 0xffff0000, v77
	v_add_f32_e32 v128, v236, v128
	v_add_f32_e32 v238, v238, v239
	v_pk_mul_f32 v[242:243], v[144:145], v[144:145]
	v_lshlrev_b32_e32 v150, 16, v78
	v_and_b32_e32 v151, 0xffff0000, v78
	v_add_f32_e32 v128, v238, v128
	v_add_f32_e32 v238, v240, v241
	v_pk_mul_f32 v[244:245], v[150:151], v[150:151]
	v_lshlrev_b32_e32 v152, 16, v79
	v_and_b32_e32 v153, 0xffff0000, v79
	v_add_f32_e32 v128, v238, v128
	v_add_f32_e32 v238, v242, v243
	v_lshlrev_b32_e32 v96, 16, v80
	v_and_b32_e32 v97, 0xffff0000, v80
	v_pk_mul_f32 v[246:247], v[152:153], v[152:153]
	v_add_f32_e32 v128, v238, v128
	v_add_f32_e32 v238, v244, v245
	v_pk_mul_f32 v[188:189], v[96:97], v[96:97]
	v_lshlrev_b32_e32 v90, 16, v81
	v_and_b32_e32 v91, 0xffff0000, v81
	v_add_f32_e32 v128, v238, v128
	v_add_f32_e32 v238, v246, v247
	v_pk_mul_f32 v[190:191], v[90:91], v[90:91]
	v_lshlrev_b32_e32 v92, 16, v82
	v_and_b32_e32 v93, 0xffff0000, v82
	v_add_f32_e32 v128, v238, v128
	v_add_f32_e32 v188, v188, v189
	v_pk_mul_f32 v[192:193], v[92:93], v[92:93]
	v_lshlrev_b32_e32 v98, 16, v83
	v_and_b32_e32 v99, 0xffff0000, v83
	v_add_f32_e32 v128, v188, v128
	v_add_f32_e32 v188, v190, v191
	v_pk_mul_f32 v[194:195], v[98:99], v[98:99]
	v_lshlrev_b32_e32 v102, 16, v122
	v_and_b32_e32 v103, 0xffff0000, v122
	v_add_f32_e32 v128, v188, v128
	v_add_f32_e32 v188, v192, v193
	v_pk_mul_f32 v[196:197], v[102:103], v[102:103]
	v_lshlrev_b32_e32 v106, 16, v123
	v_and_b32_e32 v107, 0xffff0000, v123
	v_add_f32_e32 v128, v188, v128
	v_add_f32_e32 v188, v194, v195
	v_pk_mul_f32 v[198:199], v[106:107], v[106:107]
	v_lshlrev_b32_e32 v108, 16, v124
	v_and_b32_e32 v109, 0xffff0000, v124
	v_add_f32_e32 v128, v188, v128
	v_add_f32_e32 v188, v196, v197
	v_pk_mul_f32 v[200:201], v[108:109], v[108:109]
	v_lshlrev_b32_e32 v86, 16, v125
	v_and_b32_e32 v87, 0xffff0000, v125
	v_add_f32_e32 v128, v188, v128
	v_add_f32_e32 v188, v198, v199
	v_pk_mul_f32 v[202:203], v[86:87], v[86:87]
	v_lshlrev_b32_e32 v118, 16, v48
	v_and_b32_e32 v119, 0xffff0000, v48
	v_add_f32_e32 v128, v188, v128
	v_add_f32_e32 v188, v200, v201
	v_lshlrev_b32_e32 v124, 16, v49
	v_and_b32_e32 v125, 0xffff0000, v49
	v_pk_mul_f32 v[214:215], v[118:119], v[118:119]
	v_add_f32_e32 v128, v188, v128
	v_add_f32_e32 v188, v202, v203
	v_lshlrev_b32_e32 v122, 16, v50
	v_and_b32_e32 v123, 0xffff0000, v50
	v_pk_mul_f32 v[218:219], v[124:125], v[124:125]
	v_add_f32_e32 v128, v188, v128
	v_add_f32_e32 v188, v214, v215
	v_lshlrev_b32_e32 v66, 16, v136
	v_and_b32_e32 v67, 0xffff0000, v136
	v_lshlrev_b32_e32 v72, 16, v137
	v_and_b32_e32 v73, 0xffff0000, v137
	v_lshlrev_b32_e32 v136, 16, v51
	v_and_b32_e32 v137, 0xffff0000, v51
	v_pk_mul_f32 v[220:221], v[122:123], v[122:123]
	v_add_f32_e32 v128, v188, v128
	v_add_f32_e32 v188, v218, v219
	v_lshlrev_b32_e32 v64, 16, v134
	v_and_b32_e32 v65, 0xffff0000, v134
	v_lshlrev_b32_e32 v68, 16, v135
	v_and_b32_e32 v69, 0xffff0000, v135
	v_lshlrev_b32_e32 v134, 16, v44
	v_and_b32_e32 v135, 0xffff0000, v44
	v_pk_mul_f32 v[172:173], v[136:137], v[136:137]
	v_add_f32_e32 v128, v188, v128
	v_add_f32_e32 v188, v220, v221
	v_lshlrev_b32_e32 v74, 16, v148
	v_and_b32_e32 v75, 0xffff0000, v148
	v_lshlrev_b32_e32 v82, 16, v149
	v_and_b32_e32 v83, 0xffff0000, v149
	v_lshlrev_b32_e32 v148, 16, v45
	v_and_b32_e32 v149, 0xffff0000, v45
	v_pk_mul_f32 v[174:175], v[134:135], v[134:135]
	v_add_f32_e32 v128, v188, v128
	v_add_f32_e32 v172, v172, v173
	v_lshlrev_b32_e32 v70, 16, v146
	v_and_b32_e32 v71, 0xffff0000, v146
	v_lshlrev_b32_e32 v76, 16, v147
	v_and_b32_e32 v77, 0xffff0000, v147
	v_lshlrev_b32_e32 v146, 16, v46
	v_and_b32_e32 v147, 0xffff0000, v46
	v_pk_mul_f32 v[176:177], v[148:149], v[148:149]
	v_add_f32_e32 v128, v172, v128
	v_add_f32_e32 v172, v174, v175
	v_lshlrev_b32_e32 v154, 16, v47
	v_and_b32_e32 v155, 0xffff0000, v47
	v_pk_mul_f32 v[178:179], v[146:147], v[146:147]
	v_add_f32_e32 v128, v172, v128
	v_add_f32_e32 v172, v176, v177
	v_pk_mul_f32 v[180:181], v[154:155], v[154:155]
	v_add_f32_e32 v128, v172, v128
	v_add_f32_e32 v172, v178, v179
	v_pk_mul_f32 v[210:211], v[64:65], v[64:65]
	v_and_b32_e32 v49, 0xffff0000, v40
	v_and_b32_e32 v45, 0xffff0000, v41
	v_add_f32_e32 v128, v172, v128
	v_add_f32_e32 v172, v180, v181
	v_pk_mul_f32 v[216:217], v[68:69], v[68:69]
	v_lshlrev_b32_e32 v48, 16, v40
	v_lshlrev_b32_e32 v44, 16, v41
	v_mov_b32_e32 v248, v45
	v_mov_b32_e32 v249, v49
	v_add_f32_e32 v128, v172, v128
	v_add_f32_e32 v172, v210, v211
	v_pk_mul_f32 v[222:223], v[66:67], v[66:67]
	v_lshlrev_b32_e32 v40, 16, v36
	v_and_b32_e32 v41, 0xffff0000, v36
	v_lshlrev_b32_e32 v46, 16, v37
	v_and_b32_e32 v47, 0xffff0000, v37
	v_lshlrev_b32_e32 v36, 16, v38
	v_and_b32_e32 v37, 0xffff0000, v38
	v_lshlrev_b32_e32 v50, 16, v39
	v_and_b32_e32 v51, 0xffff0000, v39
	v_lshlrev_b32_e32 v38, 16, v32
	v_and_b32_e32 v39, 0xffff0000, v32
	v_lshlrev_b32_e32 v80, 16, v33
	v_and_b32_e32 v81, 0xffff0000, v33
	v_lshlrev_b32_e32 v79, 16, v34
	v_and_b32_e32 v33, 0xffff0000, v34
	v_lshlrev_b32_e32 v78, 16, v35
	v_and_b32_e32 v32, 0xffff0000, v35
	v_mov_b32_e32 v34, v44
	v_mov_b32_e32 v35, v48
	v_pk_mul_f32 v[248:249], v[248:249], v[248:249]
	v_add_f32_e32 v128, v172, v128
	v_add_f32_e32 v172, v216, v217
	v_pk_fma_f32 v[34:35], v[34:35], v[34:35], v[248:249]
	v_pk_mul_f32 v[248:249], v[72:73], v[72:73]
	v_add_f32_e32 v128, v172, v128
; DEVINL i32x6 pk6(const f32x16& a, const f32x16& b) { return __builtin_amdgcn_cvt_scalef32_2xpk16_fp6_f32(a, b, 1.0f); }
; DEVINL float bflo(unsigned u) { return __uint_as_float(u << 16); }
; DEVINL float bfhi(unsigned u) { return __uint_as_float(u & 0xffff0000u); }
; DEVINL void qn_row(const Params& p, bf16_t* rowp) {
;     ...
;   float ss = 0.f;
; #pragma unroll
;   for (int c = 0; c < 16; ++c)
; #pragma unroll
;     for (int j = 0; j < 4; ++j) { const float a = bflo(raw[c][j]), b = bfhi(raw[c][j]); ss += a * a + b * b; }
;   const float r = rsqrtf(ss * (1.f / 128.f) + EPS);
; #pragma unroll
;   for (int ch = 0; ch < 4; ++ch) {
;     f32x16 a, b;
; #pragma unroll
;     for (int q = 0; q < 2; ++q)
; #pragma unroll
;       for (int j = 0; j < 4; ++j) {
;         const int ca = ch * 4 + q, cb = ch * 4 + 2 + q, da = ca * 8 + 2 * j, db = cb * 8 + 2 * j;
;         a[q * 8 + 2 * j] = bflo(raw[ca][j]) * r * p.qn_w[da]; a[q * 8 + 2 * j + 1] = bfhi(raw[ca][j]) * r * p.qn_w[da + 1];
;         b[q * 8 + 2 * j] = bflo(raw[cb][j]) * r * p.qn_w[db]; b[q * 8 + 2 * j + 1] = bfhi(raw[cb][j]) * r * p.qn_w[db + 1];
;       }
;     const i32x6 w = pk6(a, b);
;     u32x2* d = reinterpret_cast<u32x2*>((char*)rowp + ch * 24);
;     d[0] = u32x2{(unsigned)w[0], (unsigned)w[1]}; d[1] = u32x2{(unsigned)w[2], (unsigned)w[3]}; d[2] = u32x2{(unsigned)w[4], (unsigned)w[5]};
;   }
	v_add_f32_e32 v172, v222, v223
	v_pk_mul_f32 v[208:209], v[70:71], v[70:71]
	v_add_f32_e32 v128, v172, v128
	v_add_f32_e32 v172, v248, v249
	v_pk_mul_f32 v[204:205], v[76:77], v[76:77]
	v_add_f32_e32 v128, v172, v128
	v_add_f32_e32 v172, v208, v209
	v_pk_mul_f32 v[206:207], v[74:75], v[74:75]
	v_add_f32_e32 v128, v172, v128
	v_add_f32_e32 v172, v204, v205
	v_pk_mul_f32 v[212:213], v[82:83], v[82:83]
	v_add_f32_e32 v128, v172, v128
	v_add_f32_e32 v172, v206, v207
	v_pk_mul_f32 v[182:183], v[40:41], v[40:41]
	v_add_f32_e32 v128, v172, v128
	v_add_f32_e32 v172, v212, v213
	v_pk_mul_f32 v[184:185], v[46:47], v[46:47]
	v_add_f32_e32 v128, v172, v128
	v_add_f32_e32 v172, v182, v183
	v_pk_mul_f32 v[186:187], v[36:37], v[36:37]
	v_add_f32_e32 v128, v172, v128
	v_add_f32_e32 v172, v184, v185
	v_pk_mul_f32 v[230:231], v[50:51], v[50:51]
	v_add_f32_e32 v128, v172, v128
	v_add_f32_e32 v172, v186, v187
	v_pk_mul_f32 v[232:233], v[38:39], v[38:39]
	v_add_f32_e32 v128, v172, v128
	v_add_f32_e32 v172, v230, v231
	v_pk_mul_f32 v[234:235], v[80:81], v[80:81]
	v_add_f32_e32 v128, v172, v128
	v_add_f32_e32 v172, v232, v233
	v_pk_mul_f32 v[236:237], v[32:33], v[32:33]
	v_add_f32_e32 v128, v172, v128
	v_add_f32_e32 v172, v234, v235
	v_pk_fma_f32 v[236:237], v[78:79], v[78:79], v[236:237]
	v_add_f32_e32 v128, v172, v128
	v_add_f32_e32 v128, v237, v128
	v_add_f32_e32 v128, v236, v128
	v_add_f32_e32 v35, v35, v128
	v_add_f32_e32 v34, v34, v35
	v_add_f32_e32 v34, v116, v34
	v_add_f32_e32 v34, v117, v34
	v_add_f32_e32 v34, v120, v34
	v_add_f32_e32 v34, v121, v34
	v_add_f32_e32 v34, v126, v34
	v_add_f32_e32 v34, v127, v34
	v_fmamk_f32 v34, v34, 0x3c000000, v227
	v_mul_f32_e32 v35, 0x4b800000, v34
	v_cmp_gt_f32_e32 vcc, s46, v34
	s_nop 1
	v_cndmask_b32_e32 v34, v34, v35, vcc
	v_rsq_f32_e32 v34, v34
	s_nop 0
	v_mul_f32_e32 v35, 0x45800000, v34
	v_cndmask_b32_e32 v34, v34, v35, vcc
	v_mul_f32_e32 v34, 0x3f553b94, v34
	v_pk_mul_f32 v[116:117], v[34:35], v[156:157] op_sel_hi:[0,1]
	v_pk_mul_f32 v[120:121], v[34:35], v[158:159] op_sel_hi:[0,1]
	v_pk_mul_f32 v[126:127], v[34:35], v[160:161] op_sel_hi:[0,1]
	v_pk_mul_f32 v[156:157], v[34:35], v[162:163] op_sel_hi:[0,1]
	v_pk_mul_f32 v[158:159], v[34:35], v[164:165] op_sel_hi:[0,1]
	v_pk_mul_f32 v[160:161], v[34:35], v[166:167] op_sel_hi:[0,1]
	v_pk_mul_f32 v[162:163], v[34:35], v[168:169] op_sel_hi:[0,1]
	v_pk_mul_f32 v[164:165], v[34:35], v[170:171] op_sel_hi:[0,1]
	v_pk_mul_f32 v[84:85], v[34:35], v[84:85] op_sel_hi:[0,1]
	v_pk_mul_f32 v[88:89], v[34:35], v[88:89] op_sel_hi:[0,1]
	v_pk_mul_f32 v[94:95], v[34:35], v[94:95] op_sel_hi:[0,1]
	v_pk_mul_f32 v[100:101], v[34:35], v[100:101] op_sel_hi:[0,1]
	v_pk_mul_f32 v[104:105], v[34:35], v[104:105] op_sel_hi:[0,1]
	v_pk_mul_f32 v[110:111], v[34:35], v[110:111] op_sel_hi:[0,1]
	v_pk_mul_f32 v[112:113], v[34:35], v[112:113] op_sel_hi:[0,1]
	v_pk_mul_f32 v[114:115], v[34:35], v[114:115] op_sel_hi:[0,1]
	s_waitcnt vmcnt(0)
	v_pk_mul_f32 v[14:15], v[14:15], v[164:165]
	v_pk_mul_f32 v[12:13], v[12:13], v[162:163]
	v_pk_mul_f32 v[10:11], v[10:11], v[160:161]
	v_pk_mul_f32 v[8:9], v[8:9], v[158:159]
	v_pk_mul_f32 v[6:7], v[6:7], v[156:157]
	v_pk_mul_f32 v[4:5], v[4:5], v[126:127]
	v_pk_mul_f32 v[2:3], v[2:3], v[120:121]
	v_pk_mul_f32 v[0:1], v[0:1], v[116:117]
	v_pk_mul_f32 v[30:31], v[30:31], v[114:115]
	v_pk_mul_f32 v[28:29], v[28:29], v[112:113]
	v_pk_mul_f32 v[26:27], v[26:27], v[110:111]
	v_pk_mul_f32 v[24:25], v[24:25], v[104:105]
	v_pk_mul_f32 v[22:23], v[22:23], v[100:101]
	v_pk_mul_f32 v[20:21], v[20:21], v[94:95]
	v_pk_mul_f32 v[18:19], v[18:19], v[88:89]
	v_pk_mul_f32 v[16:17], v[16:17], v[84:85]
	v_pk_mul_f32 v[84:85], v[34:35], v[138:139] op_sel_hi:[0,1]
	v_cvt_scalef32_2xpk16_fp6_f32 v[0:5], v[0:15], v[16:31], 1.0
	flat_store_dwordx4 v[52:53], v[0:3]
	flat_store_dwordx2 v[52:53], v[4:5] offset:16
	global_load_dwordx4 v[0:3], v129, s[52:53] offset:128
	s_nop 0
	global_load_dwordx4 v[4:7], v129, s[52:53] offset:144
	global_load_dwordx4 v[8:11], v129, s[52:53] offset:160
	global_load_dwordx4 v[12:15], v129, s[52:53] offset:176
	global_load_dwordx4 v[16:19], v129, s[52:53] offset:192
	global_load_dwordx4 v[20:23], v129, s[52:53] offset:208
	global_load_dwordx4 v[24:27], v129, s[52:53] offset:224
	global_load_dwordx4 v[28:31], v129, s[52:53] offset:240
	v_pk_mul_f32 v[88:89], v[34:35], v[96:97] op_sel_hi:[0,1]
	v_pk_mul_f32 v[94:95], v[34:35], v[130:131] op_sel_hi:[0,1]
	v_pk_mul_f32 v[90:91], v[34:35], v[90:91] op_sel_hi:[0,1]
	v_pk_mul_f32 v[96:97], v[34:35], v[132:133] op_sel_hi:[0,1]
	v_pk_mul_f32 v[92:93], v[34:35], v[92:93] op_sel_hi:[0,1]
	v_pk_mul_f32 v[100:101], v[34:35], v[140:141] op_sel_hi:[0,1]
	v_pk_mul_f32 v[98:99], v[34:35], v[98:99] op_sel_hi:[0,1]
	v_pk_mul_f32 v[104:105], v[34:35], v[142:143] op_sel_hi:[0,1]
	v_pk_mul_f32 v[102:103], v[34:35], v[102:103] op_sel_hi:[0,1]
	v_pk_mul_f32 v[110:111], v[34:35], v[144:145] op_sel_hi:[0,1]
	v_pk_mul_f32 v[106:107], v[34:35], v[106:107] op_sel_hi:[0,1]
	v_pk_mul_f32 v[112:113], v[34:35], v[150:151] op_sel_hi:[0,1]
	v_pk_mul_f32 v[108:109], v[34:35], v[108:109] op_sel_hi:[0,1]
	v_pk_mul_f32 v[114:115], v[34:35], v[152:153] op_sel_hi:[0,1]
	v_pk_mul_f32 v[40:41], v[34:35], v[40:41] op_sel_hi:[0,1]
	v_pk_mul_f32 v[36:37], v[34:35], v[36:37] op_sel_hi:[0,1]
	s_waitcnt vmcnt(0)
; DEVINL i32x6 pk6(const f32x16& a, const f32x16& b) { return __builtin_amdgcn_cvt_scalef32_2xpk16_fp6_f32(a, b, 1.0f); }
; DEVINL float bflo(unsigned u) { return __uint_as_float(u << 16); }
; DEVINL float bfhi(unsigned u) { return __uint_as_float(u & 0xffff0000u); }
; DEVINL void qn_row(const Params& p, bf16_t* rowp) {
;     ...
; #pragma unroll
;   for (int ch = 0; ch < 4; ++ch) {
;     f32x16 a, b;
; #pragma unroll
;     for (int q = 0; q < 2; ++q)
; #pragma unroll
;       for (int j = 0; j < 4; ++j) {
;         const int ca = ch * 4 + q, cb = ch * 4 + 2 + q, da = ca * 8 + 2 * j, db = cb * 8 + 2 * j;
;         a[q * 8 + 2 * j] = bflo(raw[ca][j]) * r * p.qn_w[da]; a[q * 8 + 2 * j + 1] = bfhi(raw[ca][j]) * r * p.qn_w[da + 1];
;         b[q * 8 + 2 * j] = bflo(raw[cb][j]) * r * p.qn_w[db]; b[q * 8 + 2 * j + 1] = bfhi(raw[cb][j]) * r * p.qn_w[db + 1];
;       }
;     const i32x6 w = pk6(a, b);
;     u32x2* d = reinterpret_cast<u32x2*>((char*)rowp + ch * 24);
;     d[0] = u32x2{(unsigned)w[0], (unsigned)w[1]}; d[1] = u32x2{(unsigned)w[2], (unsigned)w[3]}; d[2] = u32x2{(unsigned)w[4], (unsigned)w[5]};
;   }
	v_pk_mul_f32 v[0:1], v[0:1], v[84:85]
	v_pk_mul_f32 v[84:85], v[34:35], v[86:87] op_sel_hi:[0,1]
	v_pk_mul_f32 v[2:3], v[2:3], v[94:95]
	v_pk_mul_f32 v[4:5], v[4:5], v[96:97]
	v_pk_mul_f32 v[6:7], v[6:7], v[100:101]
	v_pk_mul_f32 v[8:9], v[8:9], v[104:105]
	v_pk_mul_f32 v[10:11], v[10:11], v[110:111]
	v_pk_mul_f32 v[12:13], v[12:13], v[112:113]
	v_pk_mul_f32 v[14:15], v[114:115], v[14:15]
	v_pk_mul_f32 v[16:17], v[16:17], v[88:89]
	v_pk_mul_f32 v[18:19], v[18:19], v[90:91]
	v_pk_mul_f32 v[20:21], v[20:21], v[92:93]
	v_pk_mul_f32 v[22:23], v[22:23], v[98:99]
	v_pk_mul_f32 v[24:25], v[24:25], v[102:103]
	v_pk_mul_f32 v[26:27], v[26:27], v[106:107]
	v_pk_mul_f32 v[28:29], v[108:109], v[28:29]
	v_pk_mul_f32 v[30:31], v[84:85], v[30:31]
	v_pk_mul_f32 v[96:97], v[34:35], v[118:119] op_sel_hi:[0,1]
	v_cvt_scalef32_2xpk16_fp6_f32 v[0:5], v[0:15], v[16:31], 1.0
	flat_store_dwordx4 v[52:53], v[0:3] offset:24
	flat_store_dwordx2 v[52:53], v[4:5] offset:40
	global_load_dwordx4 v[0:3], v129, s[52:53] offset:304
	s_nop 0
	global_load_dwordx4 v[4:7], v129, s[52:53] offset:288
	global_load_dwordx4 v[14:17], v129, s[52:53] offset:272
	global_load_dwordx4 v[18:21], v129, s[52:53] offset:256
	global_load_dwordx4 v[24:27], v129, s[52:53] offset:368
	global_load_dwordx4 v[84:87], v129, s[52:53] offset:352
	global_load_dwordx4 v[88:91], v129, s[52:53] offset:336
	global_load_dwordx4 v[92:95], v129, s[52:53] offset:320
	v_pk_mul_f32 v[22:23], v[34:35], v[124:125] op_sel_hi:[0,1]
	v_pk_mul_f32 v[28:29], v[34:35], v[136:137] op_sel_hi:[0,1]
	v_pk_mul_f32 v[10:11], v[34:35], v[148:149] op_sel_hi:[0,1]
	v_pk_mul_f32 v[30:31], v[34:35], v[154:155] op_sel_hi:[0,1]
	v_pk_mul_f32 v[98:99], v[34:35], v[122:123] op_sel_hi:[0,1]
	v_pk_mul_f32 v[8:9], v[34:35], v[134:135] op_sel_hi:[0,1]
	v_pk_mul_f32 v[12:13], v[34:35], v[146:147] op_sel_hi:[0,1]
	s_waitcnt vmcnt(0)
	v_pk_mul_f32 v[12:13], v[12:13], v[0:1]
	v_pk_mul_f32 v[8:9], v[8:9], v[4:5]
	v_pk_mul_f32 v[4:5], v[98:99], v[14:15]
	v_pk_mul_f32 v[0:1], v[96:97], v[18:19]
	v_pk_mul_f32 v[14:15], v[30:31], v[2:3]
	v_pk_mul_f32 v[10:11], v[10:11], v[6:7]
	v_pk_mul_f32 v[6:7], v[28:29], v[16:17]
	v_pk_mul_f32 v[2:3], v[22:23], v[20:21]
	v_pk_mul_f32 v[18:19], v[34:35], v[68:69] op_sel_hi:[0,1]
	v_pk_mul_f32 v[22:23], v[34:35], v[72:73] op_sel_hi:[0,1]
	v_pk_mul_f32 v[68:69], v[34:35], v[76:77] op_sel_hi:[0,1]
	v_pk_mul_f32 v[30:31], v[34:35], v[82:83] op_sel_hi:[0,1]
	v_pk_mul_f32 v[16:17], v[34:35], v[64:65] op_sel_hi:[0,1]
	v_pk_mul_f32 v[20:21], v[34:35], v[66:67] op_sel_hi:[0,1]
	v_pk_mul_f32 v[64:65], v[34:35], v[70:71] op_sel_hi:[0,1]
	v_pk_mul_f32 v[28:29], v[34:35], v[74:75] op_sel_hi:[0,1]
	v_pk_mul_f32 v[28:29], v[28:29], v[24:25]
	v_pk_mul_f32 v[24:25], v[64:65], v[84:85]
	v_pk_mul_f32 v[20:21], v[20:21], v[88:89]
	v_pk_mul_f32 v[16:17], v[16:17], v[92:93]
	v_pk_mul_f32 v[30:31], v[30:31], v[26:27]
	v_pk_mul_f32 v[26:27], v[68:69], v[86:87]
	v_pk_mul_f32 v[22:23], v[22:23], v[90:91]
	v_pk_mul_f32 v[18:19], v[18:19], v[94:95]
	s_nop 0
	v_cvt_scalef32_2xpk16_fp6_f32 v[0:5], v[0:15], v[16:31], 1.0
	flat_store_dwordx4 v[52:53], v[0:3] offset:48
	flat_store_dwordx2 v[52:53], v[4:5] offset:64
	global_load_dwordx4 v[0:3], v129, s[52:53] offset:448
	s_nop 0
	global_load_dwordx4 v[4:7], v129, s[52:53] offset:464
	global_load_dwordx4 v[8:11], v129, s[52:53] offset:480
	global_load_dwordx4 v[12:15], v129, s[52:53] offset:496
	global_load_dwordx4 v[16:19], v129, s[52:53] offset:432
	global_load_dwordx4 v[20:23], v129, s[52:53] offset:416
	global_load_dwordx4 v[64:67], v129, s[52:53] offset:400
	global_load_dwordx4 v[68:71], v129, s[52:53] offset:384
	v_mov_b32_e32 v24, v60
	v_mov_b32_e32 v25, v56
	v_mov_b32_e32 v56, v61
	v_pk_mul_f32 v[24:25], v[34:35], v[24:25] op_sel_hi:[0,1]
	v_mov_b32_e32 v26, v62
	v_mov_b32_e32 v27, v58
	v_mov_b32_e32 v58, v63
	v_mov_b32_e32 v28, v42
	v_mov_b32_e32 v29, v54
	v_pk_mul_f32 v[30:31], v[34:35], v[48:49] op_sel_hi:[0,1]
	v_mov_b32_e32 v54, v43
	s_waitcnt vmcnt(0)
	v_pk_mul_f32 v[0:1], v[30:31], v[0:1]
	v_pk_mul_f32 v[4:5], v[24:25], v[4:5]
	v_pk_mul_f32 v[24:25], v[34:35], v[56:57] op_sel_hi:[0,1]
	v_pk_mul_f32 v[6:7], v[24:25], v[6:7]
	v_pk_mul_f32 v[24:25], v[34:35], v[26:27] op_sel_hi:[0,1]
	v_pk_mul_f32 v[8:9], v[24:25], v[8:9]
	v_pk_mul_f32 v[24:25], v[34:35], v[58:59] op_sel_hi:[0,1]
	v_pk_mul_f32 v[10:11], v[24:25], v[10:11]
	v_pk_mul_f32 v[24:25], v[34:35], v[28:29] op_sel_hi:[0,1]
	v_pk_mul_f32 v[30:31], v[34:35], v[44:45] op_sel_hi:[0,1]
	v_pk_mul_f32 v[12:13], v[24:25], v[12:13]
	v_mov_b32_e32 v24, v78
	v_mov_b32_e32 v25, v32
	v_mov_b32_e32 v32, v79
	v_pk_mul_f32 v[2:3], v[30:31], v[2:3]
	v_pk_mul_f32 v[44:45], v[34:35], v[46:47] op_sel_hi:[0,1]
	v_pk_mul_f32 v[46:47], v[34:35], v[50:51] op_sel_hi:[0,1]
	v_pk_mul_f32 v[26:27], v[34:35], v[80:81] op_sel_hi:[0,1]
	v_pk_mul_f32 v[30:31], v[34:35], v[24:25] op_sel_hi:[0,1]
	v_pk_mul_f32 v[24:25], v[34:35], v[38:39] op_sel_hi:[0,1]
	v_pk_mul_f32 v[28:29], v[34:35], v[32:33] op_sel_hi:[0,1]
	v_pk_mul_f32 v[32:33], v[34:35], v[54:55] op_sel_hi:[0,1]
	v_pk_mul_f32 v[28:29], v[28:29], v[16:17]
	v_pk_mul_f32 v[24:25], v[24:25], v[20:21]
	v_pk_mul_f32 v[20:21], v[36:37], v[64:65]
	v_pk_mul_f32 v[16:17], v[40:41], v[68:69]
	v_pk_mul_f32 v[30:31], v[30:31], v[18:19]
	v_pk_mul_f32 v[26:27], v[26:27], v[22:23]
	v_pk_mul_f32 v[22:23], v[46:47], v[66:67]
	v_pk_mul_f32 v[18:19], v[44:45], v[70:71]
	v_pk_mul_f32 v[14:15], v[32:33], v[14:15]
	s_nop 0
	v_cvt_scalef32_2xpk16_fp6_f32 v[0:5], v[16:31], v[0:15], 1.0
	flat_store_dwordx4 v[52:53], v[0:3] offset:72
	flat_store_dwordx2 v[52:53], v[4:5] offset:88

; DEVINL unsigned char* wsp(const Params& p) { unsigned char* w = p.ws; asm volatile("" : "+s"(w)); return w; }
; DEVINL i32x8 mk6(int a, int b, int c, int d, int e, int f) { i32x8 r = __builtin_nondeterministic_value(r); r[0] = a; r[1] = b; r[2] = c; r[3] = d; r[4] = e; r[5] = f; return r; }
; DEVINL void phase_attn(const Params& p, char* lds) {
;     ...
;   {
;     const bf16_t* QN = (const bf16_t*)(wsp(p) + OFF_QN); const bf16_t* QRp = (const bf16_t*)(wsp(p) + OFF_QR);
;     const char* K8 = (const char*)(wsp(p) + OFF_K8); const char* KP8 = (const char*)(wsp(p) + OFF_KP8); const char* V8 = (const char*)(wsp(p) + OFF_V);
;     const bf16_t* G = (const bf16_t*)p.out; bf16_t* YM = (bf16_t*)(wsp(p) + OFF_YM);
;     for (int it = blockIdx.x; it < 512; it += gridDim.x) {
;       const int h = it & 7, qb = it >> 3;
;       mla_block(p, QN + ((size_t)h * SEQ + qb * 256) * 128, QRp + ((size_t)h * SEQ + qb * 256) * 64, K8 + (size_t)h * (LP / 64) * 6144, KP8, V8 + (size_t)h * (LP / 64) * 8192,
;                 G + (size_t)qb * 256 * 1024 + h * 128, YM + (size_t)qb * 256 * 1024 + h * 128, lds, NMETA + qb * 256);
.LBB0_546:
	s_cmp_lt_i32 s76, 5
	s_cselect_b64 s[28:29], -1, 0
	s_and_b64 s[4:5], s[28:29], s[38:39]
	s_andn2_b64 vcc, exec, s[4:5]
	s_cbranch_vccnz .LBB0_620
	s_mov_b64 s[6:7], s[72:73]
	s_mov_b64 s[8:9], s[72:73]
	s_mov_b64 s[10:11], s[72:73]
	s_mov_b64 s[4:5], s[72:73]
	s_mov_b64 s[30:31], s[72:73]
	s_mov_b64 s[12:13], s[72:73]
	s_cmpk_gt_i32 s2, 0x1ff
	s_cbranch_scc1 .LBB0_583
	s_add_u32 s33, s6, 0xaa58400
	s_addc_u32 s51, s7, 0
	s_add_u32 s54, s8, 0xca58400
	s_addc_u32 s55, s9, 0
	s_add_u32 s56, s10, 0x9a18400
	s_addc_u32 s57, s11, 0
	s_add_u32 s34, s4, 0xfa58400
	s_addc_u32 s35, s5, 0
	s_add_u32 s58, s30, 0x89d8400
	s_addc_u32 s59, s31, 0
	s_add_u32 s62, s12, 0xda58400
	s_addc_u32 s63, s13, 0
	s_add_u32 s38, s4, 0xfa59000
	s_addc_u32 s39, s5, 0
	s_add_u32 s40, s4, 0xfa59c00
	s_addc_u32 s41, s5, 0
	s_add_u32 s42, s0, 0xa8
	s_addc_u32 s43, s1, 0
	s_mov_b32 s13, 0
	v_mov_b32_e32 v139, 0
	s_mov_b64 s[44:45], 0x1800
	s_mov_b64 s[46:47], 0x3000
	s_add_i32 s68, 0, 0x11000
	s_mov_b64 s[48:49], 0x2000
	v_mov_b32_e32 v162, 0x7f7f7f7f
	s_mov_b32 s69, 0x40a194f4
	s_mov_b32 s50, 1.0
	v_mov_b32_e32 v143, 0x7c7c7c7c
	v_mov_b32_e32 v163, 0xf149f2ca
	v_mov_b32_e32 v164, 0x40400000
	v_mov_b32_e32 v112, 0x38383838
	s_mov_b32 s74, s2
	s_branch .LBB0_550

; #define ISSUE_K(j) do { const int _t = (j) < NT ? (j) : NT - 1; char* _d = K_lds + ((j) & 3) * SHM_K8; if (wid < 6) GLDS(K8 + (size_t)_t * 6144 + t16u, _d + tid16); \
;     if (wid < 3) GLDS(Kp8 + (size_t)_t * 3072 + t16u, _d + 6144 + tid16); } while (0)
; #define ISSUE_V(j) do { const int _t = (j) < NT ? (j) : NT - 1; GLDS(V8 + (size_t)_t * 8192 + t16u, V_lds + ((j) & 3) * SHM_V8 + tid16); } while (0)
; #define TILE_SYNC() do { asm volatile("s_waitcnt vmcnt(0)" ::: "memory"); __syncthreads(); } while (0)
; DEVINL void mla_block(const Params& p, const bf16_t* __restrict__ Qn, const bf16_t* __restrict__ Qr, const char* __restrict__ K8, const char* __restrict__ Kp8,
;                       const char* __restrict__ V8, const bf16_t* __restrict__ Gb, bf16_t* __restrict__ Yb, char* lds, int pos0) {
;     ...
;   const int tid16 = tid * 16;
;   const unsigned t16u = (unsigned)tid16;
;     ...
;   f32x16 pA0, pA1, pB0, pB1; float mnA, mnB, alA, alB; i32x8 pa; VFrag vf; constexpr int NT = NT_MLA;
;   const i32x8 ones8 = {0x38383838, 0x38383838, 0x38383838, 0x38383838, 0x38383838, 0x38383838, 0x38383838, 0x38383838};
;   f32x16 lsum;
;     ...
;   ISSUE_K(0); ISSUE_K(1); ISSUE_K(2); ISSUE_V(0); ISSUE_V(1); TILE_SYNC();
.LBB0_559:
	s_or_b64 exec, exec, s[8:9]
	s_mul_i32 s8, s75, 0x208000
	s_add_u32 s14, s58, s8
	v_add_u32_e32 v0, 0x9000, v172
	s_addc_u32 s15, s59, 0
	v_readfirstlane_b32 s9, v0
	v_add_u32_e32 v2, 0xb000, v172
	v_lshl_add_u64 v[140:141], s[14:15], 0, v[138:139]
	s_mov_b32 m0, s9
	v_readfirstlane_b32 s9, v2
	global_load_lds_dwordx4 v[140:141], off
	v_lshl_add_u64 v[0:1], v[140:141], 0, s[48:49]
	s_mov_b32 m0, s9
	v_lshlrev_b32_e32 v170, 9, v48
	global_load_lds_dwordx4 v[0:1], off
	v_and_b32_e32 v0, 0x3fffffc0, v166
	v_lshl_add_u32 v171, v0, 2, s68
	v_add_u32_e32 v0, 0, v170
	v_lshlrev_b32_e32 v176, 3, v167
	v_lshlrev_b32_e32 v175, 4, v167
	v_add_u32_e32 v49, v0, v176
	v_add3_u32 v173, v0, v170, v175
	v_add_u32_e32 v0, 0x1000, v49
	s_waitcnt vmcnt(0)
	s_waitcnt vmcnt(0) lgkmcnt(0)
	s_barrier
; DEVINL void partialSM(f32x16& p0, f32x16& p1, float& m_reg, float& mn, float& alpha, int kvalid, int hi) {
;   constexpr float C = MLA_SCALE * 1.4426950408889634f;
;   if (kvalid < 64) {
; #pragma unroll
;     for (int r = 0; r < 16; ++r) { if (crow(r, hi) >= kvalid) p0[r] = -1e30f; if (32 + crow(r, hi) >= kvalid) p1[r] = -1e30f; }
;   }
;   float pmax = p0[0];
; #pragma unroll
;   for (int r = 1; r < 16; ++r) pmax = fmaxf(pmax, p0[r]);
; #pragma unroll
;   for (int r = 0; r < 16; ++r) pmax = fmaxf(pmax, p1[r]);
;   { auto rr = __builtin_amdgcn_permlane32_swap(__float_as_uint(pmax), __float_as_uint(pmax), false, false);
;     pmax = fmaxf(__uint_as_float(rr[0]), __uint_as_float(rr[1])); }
;   if (__builtin_expect(__all(pmax - m_reg <= THR / MLA_SCALE), 1)) { mn = m_reg; alpha = 1.f; }
;   else { mn = fmaxf(m_reg, pmax); alpha = __builtin_amdgcn_exp2f((m_reg - mn) * C); m_reg = mn; }
;   const float mnC = PSHIFT - mn * C;
;   const f32x2 C2 = {C, C}, M2 = {mnC, mnC};
; #pragma unroll
;   for (int r = 0; r < 16; r += 2) { f32x2 v = {p0[r], p0[r + 1]}; v = __builtin_elementwise_fma(v, C2, M2); p0[r] = v[0]; p0[r + 1] = v[1]; }
; #pragma unroll
;   for (int r = 0; r < 16; r += 2) { f32x2 v = {p1[r], p1[r + 1]}; v = __builtin_elementwise_fma(v, C2, M2); p1[r] = v[0]; p1[r + 1] = v[1]; }
; #pragma unroll
;   for (int r = 0; r < 16; ++r) p0[r] = __builtin_amdgcn_exp2f(p0[r]);
; }
; template <bool FUSE>
; DEVINL void qkt(f32x16& p0, f32x16& p1, const char* Ks, const i32x8* q8, int r32, int hi, f32x16& e1) {
;   p0 = f32x16{}; p1 = f32x16{};
;   const char* ka = Ks + hi * 1024 + r32 * 16; const char* kb = Ks + 4096 + hi * 512 + r32 * 8;
;   const char* ra = Ks + 6144 + hi * 1024 + r32 * 16; const char* rb = Ks + 6144 + 2048 + hi * 512 + r32 * 8;
;   u32x4 fa[3][2]; u32x2 fb[3][2];
;     ...
;   QK_LD(0, 0);
; #pragma unroll
;   for (int t = 0; t < 3; ++t) {
;     if (t + 1 < 3) QK_LD(t + 1, (t + 1) % 3);
;     const i32x8 a0 = mk6((int)fa[t][0][0], (int)fa[t][0][1], (int)fa[t][0][2], (int)fa[t][0][3], (int)fb[t][0][0], (int)fb[t][0][1]);
;     const i32x8 a1 = mk6((int)fa[t][1][0], (int)fa[t][1][1], (int)fa[t][1][2], (int)fa[t][1][3], (int)fb[t][1][0], (int)fb[t][1][1]);
;     p0 = MFMA6(a0, q8[t], p0);
;     if (FUSE) {
; #pragma unroll
;       for (int r = 0; r < 3; ++r) { const int rr = t * 6 + r; if (rr < 16) e1[rr] = __builtin_amdgcn_exp2f(e1[rr]); }
;     }
	ds_read2_b64 v[4:7], v0 offset1:32
	ds_read_b128 v[50:53], v173 offset:2048
	ds_read_b128 v[56:59], v173 offset:2560
	ds_read2_b64 v[60:63], v0 offset0:128 offset1:160
	ds_read_b128 v[16:19], v173 offset:512
	ds_read_b128 v[0:3], v173
	s_waitcnt lgkmcnt(5)
	v_mov_b32_e32 v20, v6
	v_mov_b32_e32 v21, v7
	s_waitcnt lgkmcnt(0)
	v_mfma_scale_f32_32x32x64_f8f6f4 v[32:47], v[0:5], v[120:125], 0, v162, v143 op_sel_hi:[0,0,0] cbsz:2 blgp:2
	s_mov_b32 s12, s13
	s_mov_b32 s14, s13
	s_mov_b32 s15, s13
	s_mov_b32 s16, s13
	s_mov_b32 s17, s13
	s_mov_b32 s18, s13
	s_mov_b32 s19, s13
	v_mfma_scale_f32_32x32x64_f8f6f4 v[16:31], v[16:21], v[120:125], 0, v162, v143 op_sel_hi:[0,0,0] cbsz:2 blgp:2
	s_mov_b32 s20, s13
	s_mov_b32 s21, s13
	s_mov_b32 s22, s13
	s_mov_b32 s23, s13
	s_mov_b32 s24, s13
	s_mov_b32 s25, s13
	s_mov_b32 s26, s13
	s_mov_b32 s27, s13
	v_mov_b64_e32 v[0:1], s[12:13]
	v_and_b32_e32 v169, 63, v166
	v_lshlrev_b32_e32 v174, 10, v48
	s_mov_b32 s53, 4
	v_mov_b64_e32 v[2:3], s[14:15]
	v_mov_b64_e32 v[4:5], s[16:17]
	v_mov_b64_e32 v[6:7], s[18:19]
	v_mov_b64_e32 v[8:9], s[20:21]
	v_mov_b64_e32 v[10:11], s[22:23]
	v_mov_b64_e32 v[12:13], s[24:25]
	v_mov_b64_e32 v[14:15], s[26:27]
	v_mov_b32_e32 v54, v60
	v_mov_b32_e32 v55, v61
	v_mov_b32_e32 v60, v62
	v_mov_b32_e32 v61, v63
	v_add_u32_e32 v49, 0x2000, v49
	v_mfma_scale_f32_32x32x64_f8f6f4 v[32:47], v[50:55], v[126:131], v[32:47], v162, v143 op_sel_hi:[0,0,0] cbsz:2 blgp:2
	ds_read_b128 v[50:53], v173 offset:6144
	ds_read_b128 v[62:65], v173 offset:6656
	ds_read2_b64 v[66:69], v49 offset1:32
	v_mfma_scale_f32_32x32x64_f8f6f4 v[16:31], v[56:61], v[126:131], v[16:31], v162, v143 op_sel_hi:[0,0,0] cbsz:2 blgp:2
	s_waitcnt lgkmcnt(0)
	v_mov_b32_e32 v54, v66
	v_mov_b32_e32 v55, v67
	v_mov_b32_e32 v66, v68
	v_mov_b32_e32 v67, v69
	v_mfma_scale_f32_32x32x64_f8f6f4 v[32:47], v[50:55], v[132:137], v[32:47], v162, v143 op_sel_hi:[0,0,0] cbsz:2 blgp:2
	s_nop 0
	v_mfma_scale_f32_32x32x64_f8f6f4 v[16:31], v[62:67], v[132:137], v[16:31], v162, v143 op_sel_hi:[0,0,0] cbsz:2 blgp:2
	s_nop 9
	v_max_f32_e32 v49, v33, v33
	v_max_f32_e32 v50, v32, v32
	v_max_f32_e32 v49, v50, v49
	v_max3_f32 v49, v49, v34, v35
	v_max3_f32 v49, v49, v36, v37
	v_max3_f32 v49, v49, v38, v39
	v_max3_f32 v49, v49, v40, v41
	v_max3_f32 v49, v49, v42, v43
	v_max3_f32 v49, v49, v44, v45
	v_max3_f32 v49, v49, v46, v47
	v_max3_f32 v49, v49, v16, v17
	v_max3_f32 v49, v49, v18, v19
	v_max3_f32 v49, v49, v20, v21
	v_max3_f32 v49, v49, v22, v23
	v_max3_f32 v49, v49, v24, v25
	v_max3_f32 v49, v49, v26, v27
	v_max3_f32 v49, v49, v28, v29
	v_max3_f32 v49, v49, v30, v31
	v_mov_b32_e32 v50, v49
	s_nop 1
	v_permlane32_swap_b32_e32 v49, v50
	v_max_f32_e32 v50, v50, v50
	v_max_f32_e32 v49, v49, v49
	v_max_f32_e32 v49, v49, v50
	v_add_f32_e32 v50, 0x7149f2ca, v49
	v_max_f32_e32 v49, 0xf149f2ca, v49
	v_sub_f32_e32 v51, 0xf149f2ca, v49
	v_mul_f32_e32 v51, 1.0, v51
	v_cmp_ge_f32_e32 vcc, s69, v50
	v_exp_f32_e32 v51, v51
	s_cmp_eq_u64 vcc, exec
	s_cselect_b64 vcc, -1, 0
	v_cndmask_b32_e32 v181, v49, v163, vcc
	v_fmamk_f32 v50, v181, 0xbf800000, v164
	v_pk_fma_f32 v[32:33], v[32:33], s[50:51], v[50:51] op_sel_hi:[1,0,0]
	v_pk_fma_f32 v[34:35], v[34:35], s[50:51], v[50:51] op_sel_hi:[1,0,0]
	v_pk_fma_f32 v[36:37], v[36:37], s[50:51], v[50:51] op_sel_hi:[1,0,0]
	v_pk_fma_f32 v[38:39], v[38:39], s[50:51], v[50:51] op_sel_hi:[1,0,0]
	v_pk_fma_f32 v[40:41], v[40:41], s[50:51], v[50:51] op_sel_hi:[1,0,0]
	v_pk_fma_f32 v[42:43], v[42:43], s[50:51], v[50:51] op_sel_hi:[1,0,0]
	v_pk_fma_f32 v[44:45], v[44:45], s[50:51], v[50:51] op_sel_hi:[1,0,0]
	v_pk_fma_f32 v[46:47], v[46:47], s[50:51], v[50:51] op_sel_hi:[1,0,0]
	v_exp_f32_e32 v65, v32
	v_exp_f32_e32 v197, v33
	v_exp_f32_e32 v187, v34
	v_exp_f32_e32 v189, v35
	v_exp_f32_e32 v195, v36
	v_exp_f32_e32 v196, v37
	v_exp_f32_e32 v191, v38
	v_exp_f32_e32 v192, v39
	v_exp_f32_e32 v193, v40
	v_exp_f32_e32 v194, v41
	v_exp_f32_e32 v183, v42
	v_exp_f32_e32 v184, v43
	v_exp_f32_e32 v188, v44
	v_exp_f32_e32 v190, v45
	v_exp_f32_e32 v185, v46
	v_exp_f32_e32 v186, v47
	s_add_u32 s8, s30, s8
	v_cndmask_b32_e64 v179, v51, 1.0, vcc
	v_pk_fma_f32 v[148:149], v[30:31], s[50:51], v[50:51] op_sel_hi:[1,0,0]
	v_pk_fma_f32 v[150:151], v[28:29], s[50:51], v[50:51] op_sel_hi:[1,0,0]
	v_pk_fma_f32 v[152:153], v[26:27], s[50:51], v[50:51] op_sel_hi:[1,0,0]
	v_pk_fma_f32 v[154:155], v[24:25], s[50:51], v[50:51] op_sel_hi:[1,0,0]
	v_pk_fma_f32 v[156:157], v[22:23], s[50:51], v[50:51] op_sel_hi:[1,0,0]
	v_pk_fma_f32 v[82:83], v[20:21], s[50:51], v[50:51] op_sel_hi:[1,0,0]
	v_pk_fma_f32 v[158:159], v[18:19], s[50:51], v[50:51] op_sel_hi:[1,0,0]
	v_pk_fma_f32 v[160:161], v[16:17], s[50:51], v[50:51] op_sel_hi:[1,0,0]
	v_lshlrev_b32_e32 v177, 4, v48
	s_addc_u32 s9, s31, 0
	v_mov_b64_e32 v[62:63], v[14:15]
	v_mov_b64_e32 v[30:31], v[14:15]
	v_mov_b64_e32 v[46:47], v[14:15]
	v_lshl_add_u64 v[144:145], s[34:35], 0, v[138:139]
	v_cmp_gt_u32_e64 s[6:7], 32, v169
	v_lshl_add_u32 v178, v167, 2, v171
	v_lshl_add_u64 v[146:147], s[8:9], 0, v[138:139]
	v_mov_b32_e32 v180, 0
	s_mov_b64 s[14:15], 0x89dc400
	v_mov_b64_e32 v[60:61], v[12:13]
	v_mov_b64_e32 v[58:59], v[10:11]
	v_mov_b64_e32 v[56:57], v[8:9]
	v_mov_b64_e32 v[54:55], v[6:7]
	v_mov_b64_e32 v[52:53], v[4:5]
	v_mov_b64_e32 v[50:51], v[2:3]
	v_mov_b64_e32 v[48:49], v[0:1]
	v_mov_b64_e32 v[28:29], v[12:13]
	v_mov_b64_e32 v[26:27], v[10:11]
	v_mov_b64_e32 v[24:25], v[8:9]
	v_mov_b64_e32 v[22:23], v[6:7]
	v_mov_b64_e32 v[20:21], v[4:5]
	v_mov_b64_e32 v[18:19], v[2:3]
	v_mov_b64_e32 v[16:17], v[0:1]
	v_mov_b64_e32 v[44:45], v[12:13]
	v_mov_b64_e32 v[42:43], v[10:11]
	v_mov_b64_e32 v[40:41], v[8:9]
	v_mov_b64_e32 v[38:39], v[6:7]
	v_mov_b64_e32 v[36:37], v[4:5]
	v_mov_b64_e32 v[34:35], v[2:3]
	v_mov_b64_e32 v[32:33], v[0:1]
	v_lshrrev_b32_e32 v175, 4, v169
	v_and_b32_e32 v175, 1, v175
	v_bfe_u32 v174, v169, 2, 2
	v_cmp_eq_u32_e64 s[8:9], v174, v175
	s_nop 1
	v_cndmask_b32_e64 v232, 0, v112, s[8:9]
	v_mov_b32_e32 v233, v232
	v_mov_b32_e32 v234, v232
	v_mov_b32_e32 v235, v232
	v_mov_b32_e32 v236, v232
	v_mov_b32_e32 v237, v232
	v_mov_b32_e32 v238, v232
	v_mov_b32_e32 v239, v232
	v_add_u32_e32 v176, v170, v176
	v_add_u32_e32 v176, 0x1000, v176
	v_add_u32_e32 v174, 0x2400, v173
	v_add_u32_e32 v175, 0x2400, v176
	ds_read_b128 v[204:207], v174
	ds_read_b64 v[208:209], v175
	ds_read_b128 v[216:219], v174 offset:512
	ds_read_b64 v[220:221], v175 offset:256
	s_lshl_b32 s78, s3, 4
	s_add_i32 s79, s78, 0x9000
	s_mul_i32 s80, s75, 0x186000
	s_add_u32 s80, s56, s80
	s_addc_u32 s81, s57, 0
	s_mov_b64 s[82:83], s[34:35]
	s_mul_i32 s84, s75, 0x208000
	s_add_u32 s84, s58, s84
	s_addc_u32 s85, s59, 0
	v_lshlrev_b32_e32 v231, 4, v169
	v_mov_b32_e32 v227, v181
	v_fmamk_f32 v230, v181, 0xbf800000, v164
	v_add_u32_e32 v140, 0x8000, v173
	s_cmp_ge_u32 s3, 0x100
	s_cbranch_scc1 .Lprio_skip
	s_setprio 2

; DEVINL int crow(int r, int hi) { return (r & 3) + 8 * (r >> 2) + 4 * hi; }
; #define SBAR() __builtin_amdgcn_sched_barrier(0)
; #define MFMA8(A, B, C) __builtin_amdgcn_mfma_scale_f32_32x32x64_f8f6f4(A, B, C, 0, 0, 0, 0x7f7f7f7f, 0, 0x7f7f7f7f)
; #define PVM(db) do { const i32x8 b = {(int)f.v[db][0][0], (int)f.v[db][0][1], (int)f.v[db][0][2], (int)f.v[db][0][3], (int)f.v[db][1][0], (int)f.v[db][1][1], (int)f.v[db][1][2], (int)f.v[db][1][3]}; \
;     o[db] = MFMA8(pa, b, o[db]); } while (0)
; DEVINL void pv_psm(f32x16* o, const VFrag& f, const i32x8& pa, f32x16& lsum, const i32x8& ones8,
;                    f32x16& p0, f32x16& p1, float& m_reg, float& mn, float& alpha, int kvalid, int hi) {
;   constexpr float C = MLA_SCALE * 1.4426950408889634f;
;     ...
;   if (kvalid < 64) {
; #pragma unroll
;     for (int r = 0; r < 16; ++r) { if (crow(r, hi) >= kvalid) p0[r] = -1e30f; if (32 + crow(r, hi) >= kvalid) p1[r] = -1e30f; }
;   }
;   PVM(0);
;   float pmax = p0[0];
; #pragma unroll
;   for (int r = 1; r < 16; ++r) pmax = fmaxf(pmax, p0[r]);
;   SBAR();
;   PVM(1);
; #pragma unroll
;   for (int r = 0; r < 16; ++r) pmax = fmaxf(pmax, p1[r]);
;   { auto rr = __builtin_amdgcn_permlane32_swap(__float_as_uint(pmax), __float_as_uint(pmax), false, false);
;     pmax = fmaxf(__uint_as_float(rr[0]), __uint_as_float(rr[1])); }
;   SBAR();
;   PVM(2);
;   if (__builtin_expect(__all(pmax - m_reg <= THR / MLA_SCALE), 1)) { mn = m_reg; alpha = 1.f; }
;   else { mn = fmaxf(m_reg, pmax); alpha = __builtin_amdgcn_exp2f((m_reg - mn) * C); m_reg = mn; }
;   const float mnC = PSHIFT - mn * C;
;   const f32x2 C2 = {C, C}, M2 = {mnC, mnC};
; #pragma unroll
;   for (int r = 0; r < 16; r += 2) { f32x2 v = {p0[r], p0[r + 1]}; v = __builtin_elementwise_fma(v, C2, M2); p0[r] = v[0]; p0[r + 1] = v[1]; }
;   SBAR();
;   PVM(3);
; #pragma unroll
;   for (int r = 0; r < 16; r += 2) { f32x2 v = {p1[r], p1[r + 1]}; v = __builtin_elementwise_fma(v, C2, M2); p1[r] = v[0]; p1[r + 1] = v[1]; }
; #pragma unroll
;   for (int r = 0; r < 8; ++r) p0[r] = __builtin_amdgcn_exp2f(p0[r]);
;   SBAR();
;   lsum = MFMA8(ones8, pa, (f32x16{}));
; #pragma unroll
;   for (int r = 8; r < 16; ++r) p0[r] = __builtin_amdgcn_exp2f(p0[r]);
;   SBAR();
;     ...
; }
.Ldma_done:
	ds_read_b128 v[114:117], v173 offset:11264
	ds_read_b128 v[198:201], v173 offset:11776
	ds_read_b64 v[118:119], v176 offset:10240
	ds_read_b64 v[202:203], v176 offset:10496
	v_exp_f32_e32 v182, v82
	s_waitcnt lgkmcnt(4)
	v_exp_f32_e32 v214, v83
	v_mfma_scale_f32_32x32x64_f8f6f4 v[96:111], v[204:209], v[120:125], 0, v162, v143 op_sel_hi:[0,0,0] cbsz:2 blgp:2
	v_exp_f32_e32 v160, v160
	v_exp_f32_e32 v161, v161
	v_exp_f32_e32 v158, v158
	v_exp_f32_e32 v159, v159
	v_mfma_scale_f32_32x32x64_f8f6f4 v[80:95], v[216:221], v[120:125], 0, v162, v143 op_sel_hi:[0,0,0] cbsz:2 blgp:2
	ds_read_b128 v[66:69], v173 offset:15360
	ds_read_b128 v[72:75], v173 offset:15872
	ds_read_b64 v[70:71], v176 offset:13312
	ds_read_b64 v[76:77], v176 offset:13568
	s_waitcnt lgkmcnt(4)
	v_mfma_scale_f32_32x32x64_f8f6f4 v[96:111], v[114:119], v[126:131], v[96:111], v162, v143 op_sel_hi:[0,0,0] cbsz:2 blgp:2
	v_exp_f32_e32 v113, v156
	v_exp_f32_e32 v114, v157
	v_exp_f32_e32 v115, v154
	v_exp_f32_e32 v116, v155
	v_exp_f32_e32 v117, v152
	v_mfma_scale_f32_32x32x64_f8f6f4 v[80:95], v[198:203], v[126:131], v[80:95], v162, v143 op_sel_hi:[0,0,0] cbsz:2 blgp:2
	v_exp_f32_e32 v118, v153
	s_waitcnt lgkmcnt(0)
	v_exp_f32_e32 v119, v150
	v_mfma_scale_f32_32x32x64_f8f6f4 v[96:111], v[66:71], v[132:137], v[96:111], v162, v143 op_sel_hi:[0,0,0] cbsz:2 blgp:2
	v_exp_f32_e32 v156, v151
	v_exp_f32_e32 v157, v148
	v_exp_f32_e32 v215, v149
	v_mfma_scale_f32_32x32x64_f8f6f4 v[80:95], v[72:77], v[132:137], v[80:95], v162, v143 op_sel_hi:[0,0,0] cbsz:2 blgp:2
	ds_read_b128 v[72:75], v140 offset:4096
	ds_read_b128 v[76:79], v140 offset:4608
	ds_read_b128 v[148:151], v140 offset:6144
	ds_read_b128 v[152:155], v140 offset:6656
	ds_read_b128 v[198:201], v140 offset:8192
	ds_read_b128 v[202:205], v140 offset:8704
	ds_read_b128 v[206:209], v140 offset:10240
	ds_read_b128 v[210:213], v140 offset:10752
	v_cvt_pk_fp8_f32 v64, v65, v197
	v_cvt_pk_fp8_f32 v68, v160, v161
	v_cvt_pk_fp8_f32 v65, v195, v196
	v_cvt_pk_fp8_f32 v69, v182, v214
	v_cvt_pk_fp8_f32 v66, v193, v194
	v_cvt_pk_fp8_f32 v70, v115, v116
	v_cvt_pk_fp8_f32 v67, v188, v190
	v_cvt_pk_fp8_f32 v71, v119, v156
	v_cvt_pk_fp8_f32 v64, v187, v189 op_sel:[0,0,1]
	v_cvt_pk_fp8_f32 v68, v158, v159 op_sel:[0,0,1]
	v_cvt_pk_fp8_f32 v65, v191, v192 op_sel:[0,0,1]
	v_cvt_pk_fp8_f32 v69, v113, v114 op_sel:[0,0,1]
	v_cvt_pk_fp8_f32 v66, v183, v184 op_sel:[0,0,1]
	v_cvt_pk_fp8_f32 v70, v117, v118 op_sel:[0,0,1]
	v_cvt_pk_fp8_f32 v67, v185, v186 op_sel:[0,0,1]
	v_cvt_pk_fp8_f32 v71, v157, v215 op_sel:[0,0,1]
	s_waitcnt lgkmcnt(0)
	s_nop 0
	v_mfma_scale_f32_32x32x64_f8f6f4 v[0:15], v[64:71], v[72:79], v[0:15], v162, v162 op_sel_hi:[0,0,0]
	v_max_f32_e32 v113, v96, v97
	v_max3_f32 v113, v113, v98, v99
	v_max3_f32 v113, v113, v100, v101
	v_max3_f32 v113, v113, v102, v103
	v_max3_f32 v113, v113, v104, v105
	v_max3_f32 v113, v113, v106, v107
	v_max3_f32 v113, v113, v108, v109
	v_max3_f32 v113, v113, v110, v111
	v_mfma_scale_f32_32x32x64_f8f6f4 v[48:63], v[64:71], v[148:155], v[48:63], v162, v162 op_sel_hi:[0,0,0]
	v_max3_f32 v72, v113, v80, v81
	v_max3_f32 v72, v72, v82, v83
	v_max3_f32 v72, v72, v84, v85
	v_max3_f32 v72, v72, v86, v87
	v_max3_f32 v72, v72, v88, v89
	v_max3_f32 v72, v72, v90, v91
	v_max3_f32 v72, v72, v92, v93
	v_max3_f32 v72, v72, v94, v95
	v_mov_b32_e32 v73, v72
	s_nop 1
	v_permlane32_swap_b32_e32 v72, v73
	v_max_f32_e32 v72, v72, v73
	v_mfma_scale_f32_32x32x64_f8f6f4 v[16:31], v[64:71], v[198:205], v[16:31], v162, v162 op_sel_hi:[0,0,0]
	v_sub_f32_e32 v73, v72, v227
	v_cmp_ge_f32_e32 vcc, s69, v73
	s_cmp_eq_u64 vcc, exec
	s_cselect_b64 s[8:9], -1, 0
	v_mov_b32_e32 v182, 1.0
	v_mfma_scale_f32_32x32x64_f8f6f4 v[32:47], v[64:71], v[206:213], v[32:47], v162, v162 op_sel_hi:[0,0,0]
	v_mfma_scale_f32_16x16x128_f8f6f4 v[240:243], v[232:239], v[64:71], 0, v162, v162 op_sel_hi:[0,0,0]
	ds_read_b128 v[200:203], v173 offset:18432
	ds_read_b64 v[204:205], v176 offset:18432
	ds_read_b128 v[206:209], v173 offset:18944
	ds_read_b64 v[210:211], v176 offset:18688
	s_and_b64 vcc, exec, s[8:9]
	s_cbranch_vccnz .LBB0_572
	v_max_f32_e32 v148, v227, v72
	v_sub_f32_e32 v72, v227, v148
	v_mul_f32_e32 v72, 1.0, v72
	v_exp_f32_e32 v182, v72
	v_mov_b32_e32 v227, v148
	v_fmamk_f32 v230, v148, 0xbf800000, v164
	s_and_saveexec_b64 s[16:17], s[6:7]
	ds_write_b32 v178, v182 offset:128
	s_or_b64 exec, exec, s[16:17]
	s_waitcnt lgkmcnt(0)
	v_add_u32_e32 v113, v171, v177
	ds_read_b128 v[72:75], v113 offset:224
	ds_read_b128 v[76:79], v113 offset:192
	ds_read_b128 v[114:117], v113 offset:160
	ds_read_b128 v[150:153], v113 offset:128
	s_waitcnt lgkmcnt(0)
	v_pk_mul_f32 v[12:13], v[12:13], v[72:73]
	v_pk_mul_f32 v[8:9], v[8:9], v[76:77]
	v_pk_mul_f32 v[4:5], v[4:5], v[114:115]
	v_pk_mul_f32 v[14:15], v[14:15], v[74:75]
	v_pk_mul_f32 v[10:11], v[10:11], v[78:79]
	v_pk_mul_f32 v[6:7], v[6:7], v[116:117]
	v_pk_mul_f32 v[2:3], v[2:3], v[152:153]
	v_pk_mul_f32 v[0:1], v[0:1], v[150:151]
	v_pk_mul_f32 v[60:61], v[60:61], v[72:73]
	v_pk_mul_f32 v[56:57], v[56:57], v[76:77]
	v_pk_mul_f32 v[52:53], v[52:53], v[114:115]
	v_pk_mul_f32 v[62:63], v[62:63], v[74:75]
	v_pk_mul_f32 v[58:59], v[58:59], v[78:79]
	v_pk_mul_f32 v[54:55], v[54:55], v[116:117]
	v_pk_mul_f32 v[50:51], v[50:51], v[152:153]
	v_pk_mul_f32 v[48:49], v[48:49], v[150:151]
	v_pk_mul_f32 v[28:29], v[28:29], v[72:73]
	v_pk_mul_f32 v[24:25], v[24:25], v[76:77]
	v_pk_mul_f32 v[20:21], v[20:21], v[114:115]
	v_pk_mul_f32 v[30:31], v[30:31], v[74:75]
	v_pk_mul_f32 v[26:27], v[26:27], v[78:79]
	v_pk_mul_f32 v[22:23], v[22:23], v[116:117]
	v_pk_mul_f32 v[18:19], v[18:19], v[152:153]
	v_pk_mul_f32 v[16:17], v[16:17], v[150:151]
	v_pk_mul_f32 v[44:45], v[44:45], v[72:73]
	v_pk_mul_f32 v[40:41], v[40:41], v[76:77]
	v_pk_mul_f32 v[36:37], v[36:37], v[114:115]
	v_pk_mul_f32 v[46:47], v[46:47], v[74:75]
	v_pk_mul_f32 v[42:43], v[42:43], v[78:79]
	v_pk_mul_f32 v[38:39], v[38:39], v[116:117]
	v_pk_mul_f32 v[34:35], v[34:35], v[152:153]
	v_pk_mul_f32 v[32:33], v[32:33], v[150:151]
; #define SBAR() __builtin_amdgcn_sched_barrier(0)
; DEVINL i32x8 mk6(int a, int b, int c, int d, int e, int f) { i32x8 r = __builtin_nondeterministic_value(r); r[0] = a; r[1] = b; r[2] = c; r[3] = d; r[4] = e; r[5] = f; return r; }
; #define MFMA6(A, B, C) __builtin_amdgcn_mfma_scale_f32_32x32x64_f8f6f4(A, B, C, 2, 2, 0, 0x7f7f7f7f, 0, 0x7f7f7f7f)
; template <bool FUSE>
; DEVINL void qkt(f32x16& p0, f32x16& p1, const char* Ks, const i32x8* q8, int r32, int hi, f32x16& e1) {
;   p0 = f32x16{}; p1 = f32x16{};
;   const char* ka = Ks + hi * 1024 + r32 * 16; const char* kb = Ks + 4096 + hi * 512 + r32 * 8;
;   const char* ra = Ks + 6144 + hi * 1024 + r32 * 16; const char* rb = Ks + 6144 + 2048 + hi * 512 + r32 * 8;
;   u32x4 fa[3][2]; u32x2 fb[3][2];
;     ...
;   QK_LD(0, 0);
; #pragma unroll
;   for (int t = 0; t < 3; ++t) {
;     if (t + 1 < 3) QK_LD(t + 1, (t + 1) % 3);
;     const i32x8 a0 = mk6((int)fa[t][0][0], (int)fa[t][0][1], (int)fa[t][0][2], (int)fa[t][0][3], (int)fb[t][0][0], (int)fb[t][0][1]);
;     const i32x8 a1 = mk6((int)fa[t][1][0], (int)fa[t][1][1], (int)fa[t][1][2], (int)fa[t][1][3], (int)fb[t][1][0], (int)fb[t][1][1]);
;     p0 = MFMA6(a0, q8[t], p0);
;     if (FUSE) {
; #pragma unroll
;       for (int r = 0; r < 3; ++r) { const int rr = t * 6 + r; if (rr < 16) e1[rr] = __builtin_amdgcn_exp2f(e1[rr]); }
;     }
;     p1 = MFMA6(a1, q8[t], p1);
;     if (FUSE) {
; #pragma unroll
;       for (int r = 3; r < 6; ++r) { const int rr = t * 6 + r; if (rr < 16) e1[rr] = __builtin_amdgcn_exp2f(e1[rr]); }
;     }
;     SBAR();
;   }
;     ...
; }
; DEVINL void pv_load(VFrag& f, const char* Vs, int r32, int hi) {
;   const char* vb = Vs + hi * 1024 + r32 * 16;
; #pragma unroll
;   for (int db = 0; db < 4; ++db) { f.v[db][0] = *reinterpret_cast<const u32x4*>(vb + db * 2048); f.v[db][1] = *reinterpret_cast<const u32x4*>(vb + db * 2048 + 512); }
; }
.LBB0_572:
	v_pk_fma_f32 v[76:77], v[104:105], s[50:51], v[230:231] op_sel_hi:[1,0,0]
	v_pk_fma_f32 v[68:69], v[96:97], s[50:51], v[230:231] op_sel_hi:[1,0,0]
	v_exp_f32_e32 v198, v77
	v_pk_fma_f32 v[70:71], v[98:99], s[50:51], v[230:231] op_sel_hi:[1,0,0]
	v_pk_fma_f32 v[72:73], v[100:101], s[50:51], v[230:231] op_sel_hi:[1,0,0]
	v_pk_fma_f32 v[74:75], v[102:103], s[50:51], v[230:231] op_sel_hi:[1,0,0]
	v_pk_fma_f32 v[78:79], v[106:107], s[50:51], v[230:231] op_sel_hi:[1,0,0]
	v_pk_fma_f32 v[96:97], v[108:109], s[50:51], v[230:231] op_sel_hi:[1,0,0]
	v_pk_fma_f32 v[98:99], v[110:111], s[50:51], v[230:231] op_sel_hi:[1,0,0]
	v_pk_fma_f32 v[102:103], v[80:81], s[50:51], v[230:231] op_sel_hi:[1,0,0]
	v_pk_fma_f32 v[114:115], v[82:83], s[50:51], v[230:231] op_sel_hi:[1,0,0]
	v_pk_fma_f32 v[116:117], v[84:85], s[50:51], v[230:231] op_sel_hi:[1,0,0]
	v_pk_fma_f32 v[228:229], v[86:87], s[50:51], v[230:231] op_sel_hi:[1,0,0]
	v_pk_fma_f32 v[156:157], v[88:89], s[50:51], v[230:231] op_sel_hi:[1,0,0]
	v_exp_f32_e32 v113, v68
	v_exp_f32_e32 v181, v69
	v_exp_f32_e32 v183, v70
	v_exp_f32_e32 v192, v71
	v_exp_f32_e32 v193, v72
	v_exp_f32_e32 v194, v73
	v_exp_f32_e32 v195, v74
	v_exp_f32_e32 v196, v75
	v_exp_f32_e32 v197, v76
	v_exp_f32_e32 v199, v78
	v_exp_f32_e32 v216, v79
	v_exp_f32_e32 v217, v96
	v_exp_f32_e32 v218, v97
	v_exp_f32_e32 v219, v98
	v_exp_f32_e32 v220, v99
	v_pk_fma_f32 v[158:159], v[90:91], s[50:51], v[230:231] op_sel_hi:[1,0,0]
	v_pk_fma_f32 v[160:161], v[92:93], s[50:51], v[230:231] op_sel_hi:[1,0,0]
	v_pk_fma_f32 v[184:185], v[94:95], s[50:51], v[230:231] op_sel_hi:[1,0,0]
	ds_read_b128 v[98:101], v173 offset:20480
	ds_read_b128 v[104:107], v173 offset:20992
	v_exp_f32_e32 v221, v102
	v_exp_f32_e32 v222, v103
	ds_read_b64 v[102:103], v176 offset:19456
	ds_read_b64 v[108:109], v176 offset:19712
	s_waitcnt lgkmcnt(4)
	v_mfma_scale_f32_32x32x64_f8f6f4 v[66:81], v[200:205], v[120:125], 0, v162, v143 op_sel_hi:[0,0,0] cbsz:2 blgp:2
	v_exp_f32_e32 v223, v114
	v_exp_f32_e32 v224, v115
	v_exp_f32_e32 v225, v116
	v_exp_f32_e32 v226, v117
	v_mfma_scale_f32_32x32x64_f8f6f4 v[82:97], v[206:211], v[120:125], 0, v162, v143 op_sel_hi:[0,0,0] cbsz:2 blgp:2
	ds_read_b128 v[114:117], v173 offset:24576
	ds_read_b128 v[148:151], v173 offset:25088
	ds_read_b64 v[118:119], v176 offset:22528
	ds_read_b64 v[152:153], v176 offset:22784
	s_waitcnt lgkmcnt(4)
	v_mfma_scale_f32_32x32x64_f8f6f4 v[66:81], v[98:103], v[126:131], v[66:81], v162, v143 op_sel_hi:[0,0,0] cbsz:2 blgp:2
	v_exp_f32_e32 v100, v228
	v_exp_f32_e32 v101, v229
	v_exp_f32_e32 v110, v156
	v_exp_f32_e32 v111, v157
	v_exp_f32_e32 v156, v158
	v_exp_f32_e32 v157, v159
	v_mfma_scale_f32_32x32x64_f8f6f4 v[82:97], v[104:109], v[126:131], v[82:97], v162, v143 op_sel_hi:[0,0,0] cbsz:2 blgp:2
	s_waitcnt lgkmcnt(0)
	v_exp_f32_e32 v106, v160
	v_mfma_scale_f32_32x32x64_f8f6f4 v[66:81], v[114:119], v[132:137], v[66:81], v162, v143 op_sel_hi:[0,0,0] cbsz:2 blgp:2
	v_exp_f32_e32 v107, v161
	v_exp_f32_e32 v108, v184
	v_exp_f32_e32 v109, v185
	v_mfma_scale_f32_32x32x64_f8f6f4 v[82:97], v[148:153], v[132:137], v[82:97], v162, v143 op_sel_hi:[0,0,0] cbsz:2 blgp:2
	ds_read_b128 v[148:151], v140 offset:12288
	ds_read_b128 v[152:155], v140 offset:12800
	ds_read_b128 v[184:187], v140 offset:14336
	ds_read_b128 v[188:191], v140 offset:14848
	ds_read_b128 v[200:203], v140 offset:16384
	ds_read_b128 v[204:207], v140 offset:16896
	ds_read_b128 v[208:211], v140 offset:18432
	ds_read_b128 v[212:215], v140 offset:18944
	v_cvt_pk_fp8_f32 v103, v225, v226
	v_cvt_pk_fp8_f32 v98, v113, v181
	v_cvt_pk_fp8_f32 v102, v221, v222
	v_cvt_pk_fp8_f32 v99, v193, v194
	v_cvt_pk_fp8_f32 v103, v100, v101 op_sel:[0,0,1]
	v_cvt_pk_fp8_f32 v100, v197, v198
	v_cvt_pk_fp8_f32 v104, v110, v111
	v_cvt_pk_fp8_f32 v101, v217, v218
	v_cvt_pk_fp8_f32 v105, v106, v107
	v_cvt_pk_fp8_f32 v98, v183, v192 op_sel:[0,0,1]
	v_cvt_pk_fp8_f32 v102, v223, v224 op_sel:[0,0,1]
	v_cvt_pk_fp8_f32 v99, v195, v196 op_sel:[0,0,1]
	v_cvt_pk_fp8_f32 v100, v199, v216 op_sel:[0,0,1]
	v_cvt_pk_fp8_f32 v104, v156, v157 op_sel:[0,0,1]
	v_cvt_pk_fp8_f32 v101, v219, v220 op_sel:[0,0,1]
	v_cvt_pk_fp8_f32 v105, v108, v109 op_sel:[0,0,1]
	s_waitcnt lgkmcnt(0)
	s_nop 0
	v_mfma_scale_f32_32x32x64_f8f6f4 v[0:15], v[98:105], v[148:155], v[0:15], v162, v162 op_sel_hi:[0,0,0]
	v_max_f32_e32 v241, v66, v67
	v_max3_f32 v241, v241, v68, v69
	v_max3_f32 v241, v241, v70, v71
	v_max3_f32 v241, v241, v72, v73
	v_max3_f32 v241, v241, v74, v75
	v_max3_f32 v241, v241, v76, v77
	v_max3_f32 v241, v241, v78, v79
	v_max3_f32 v241, v241, v80, v81
	v_mfma_scale_f32_32x32x64_f8f6f4 v[48:63], v[98:105], v[184:191], v[48:63], v162, v162 op_sel_hi:[0,0,0]
	v_max3_f32 v241, v241, v82, v83
	v_max3_f32 v241, v241, v84, v85
	v_max3_f32 v241, v241, v86, v87
	v_max3_f32 v241, v241, v88, v89
	v_max3_f32 v241, v241, v90, v91
	v_max3_f32 v241, v241, v92, v93
	v_max3_f32 v241, v241, v94, v95
	v_max3_f32 v241, v241, v96, v97
	v_mov_b32_e32 v242, v241
	s_nop 1
	v_permlane32_swap_b32_e32 v241, v242
	v_max_f32_e32 v241, v241, v242
	v_mfma_scale_f32_32x32x64_f8f6f4 v[16:31], v[98:105], v[200:207], v[16:31], v162, v162 op_sel_hi:[0,0,0]
	v_sub_f32_e32 v242, v241, v227
	v_cmp_ge_f32_e32 vcc, s69, v242
	s_cmp_eq_u64 vcc, exec
	s_cselect_b64 s[8:9], -1, 0
	v_mov_b32_e32 v198, 1.0
	v_mfma_scale_f32_32x32x64_f8f6f4 v[32:47], v[98:105], v[208:215], v[32:47], v162, v162 op_sel_hi:[0,0,0]
	s_waitcnt vmcnt(0)
	s_waitcnt vmcnt(0)
	s_barrier
; DEVINL void pv_psm(f32x16* o, const VFrag& f, const i32x8& pa, f32x16& lsum, const i32x8& ones8,
;                    f32x16& p0, f32x16& p1, float& m_reg, float& mn, float& alpha, int kvalid, int hi) {
;     ...
;   if (__builtin_expect(__all(pmax - m_reg <= THR / MLA_SCALE), 1)) { mn = m_reg; alpha = 1.f; }
;   else { mn = fmaxf(m_reg, pmax); alpha = __builtin_amdgcn_exp2f((m_reg - mn) * C); m_reg = mn; }
;   const float mnC = PSHIFT - mn * C;
	s_and_b64 vcc, exec, s[8:9]
	s_cbranch_vccnz .LBB0_576
	v_max_f32_e32 v241, v227, v241
	v_sub_f32_e32 v243, v227, v241
	v_mul_f32_e32 v243, 1.0, v243
	v_exp_f32_e32 v198, v243
	v_mov_b32_e32 v227, v241
	v_fmamk_f32 v230, v241, 0xbf800000, v164
	s_and_saveexec_b64 s[16:17], s[6:7]
	ds_write_b32 v178, v198 offset:128
	s_or_b64 exec, exec, s[16:17]
	s_waitcnt lgkmcnt(0)
	v_add_u32_e32 v242, v171, v177
	ds_read_b128 v[244:247], v242 offset:224
	ds_read_b128 v[116:119], v242 offset:192
	ds_read_b128 v[148:151], v242 offset:160
	ds_read_b128 v[152:155], v242 offset:128
	s_waitcnt lgkmcnt(3)
	v_pk_mul_f32 v[12:13], v[12:13], v[244:245]
	s_waitcnt lgkmcnt(2)
	v_pk_mul_f32 v[8:9], v[8:9], v[116:117]
	s_waitcnt lgkmcnt(1)
	v_pk_mul_f32 v[4:5], v[4:5], v[148:149]
	v_pk_mul_f32 v[14:15], v[14:15], v[246:247]
	v_pk_mul_f32 v[10:11], v[10:11], v[118:119]
	v_pk_mul_f32 v[6:7], v[6:7], v[150:151]
	s_waitcnt lgkmcnt(0)
	v_pk_mul_f32 v[2:3], v[2:3], v[154:155]
	v_pk_mul_f32 v[0:1], v[0:1], v[152:153]
	v_pk_mul_f32 v[60:61], v[60:61], v[244:245]
	v_pk_mul_f32 v[56:57], v[56:57], v[116:117]
	v_pk_mul_f32 v[52:53], v[52:53], v[148:149]
	v_pk_mul_f32 v[62:63], v[62:63], v[246:247]
	v_pk_mul_f32 v[58:59], v[58:59], v[118:119]
	v_pk_mul_f32 v[54:55], v[54:55], v[150:151]
	v_pk_mul_f32 v[50:51], v[50:51], v[154:155]
	v_pk_mul_f32 v[48:49], v[48:49], v[152:153]
	v_pk_mul_f32 v[28:29], v[28:29], v[244:245]
	v_pk_mul_f32 v[24:25], v[24:25], v[116:117]
	v_pk_mul_f32 v[20:21], v[20:21], v[148:149]
	v_pk_mul_f32 v[30:31], v[30:31], v[246:247]
	v_pk_mul_f32 v[26:27], v[26:27], v[118:119]
	v_pk_mul_f32 v[22:23], v[22:23], v[150:151]
	v_pk_mul_f32 v[18:19], v[18:19], v[154:155]
	v_pk_mul_f32 v[16:17], v[16:17], v[152:153]
	v_pk_mul_f32 v[44:45], v[44:45], v[244:245]
	v_pk_mul_f32 v[40:41], v[40:41], v[116:117]
	v_pk_mul_f32 v[36:37], v[36:37], v[148:149]
	v_pk_mul_f32 v[46:47], v[46:47], v[246:247]
	v_pk_mul_f32 v[42:43], v[42:43], v[118:119]
	v_pk_mul_f32 v[38:39], v[38:39], v[150:151]
	v_pk_mul_f32 v[34:35], v[34:35], v[154:155]
	v_pk_mul_f32 v[32:33], v[32:33], v[152:153]

; template <bool FUSE>
; DEVINL void qkt(f32x16& p0, f32x16& p1, const char* Ks, const i32x8* q8, int r32, int hi, f32x16& e1) {
;   p0 = f32x16{}; p1 = f32x16{};
;   const char* ka = Ks + hi * 1024 + r32 * 16; const char* kb = Ks + 4096 + hi * 512 + r32 * 8;
;   const char* ra = Ks + 6144 + hi * 1024 + r32 * 16; const char* rb = Ks + 6144 + 2048 + hi * 512 + r32 * 8;
;   u32x4 fa[3][2]; u32x2 fb[3][2];
;     ...
;   QK_LD(0, 0);
; #pragma unroll
;   for (int t = 0; t < 3; ++t) {
;     if (t + 1 < 3) QK_LD(t + 1, (t + 1) % 3);
;     const i32x8 a0 = mk6((int)fa[t][0][0], (int)fa[t][0][1], (int)fa[t][0][2], (int)fa[t][0][3], (int)fb[t][0][0], (int)fb[t][0][1]);
;     const i32x8 a1 = mk6((int)fa[t][1][0], (int)fa[t][1][1], (int)fa[t][1][2], (int)fa[t][1][3], (int)fb[t][1][0], (int)fb[t][1][1]);
;     p0 = MFMA6(a0, q8[t], p0);
;     if (FUSE) {
; #pragma unroll
;       for (int r = 0; r < 3; ++r) { const int rr = t * 6 + r; if (rr < 16) e1[rr] = __builtin_amdgcn_exp2f(e1[rr]); }
;     }
;     p1 = MFMA6(a1, q8[t], p1);
;     if (FUSE) {
; #pragma unroll
;       for (int r = 3; r < 6; ++r) { const int rr = t * 6 + r; if (rr < 16) e1[rr] = __builtin_amdgcn_exp2f(e1[rr]); }
;     }
;     SBAR();
;   }
; DEVINL void pv_psm(f32x16* o, const VFrag& f, const i32x8& pa, f32x16& lsum, const i32x8& ones8,
;                    f32x16& p0, f32x16& p1, float& m_reg, float& mn, float& alpha, int kvalid, int hi) {
;   constexpr float C = MLA_SCALE * 1.4426950408889634f;
;     ...
;   if (kvalid < 64) {
; #pragma unroll
;     for (int r = 0; r < 16; ++r) { if (crow(r, hi) >= kvalid) p0[r] = -1e30f; if (32 + crow(r, hi) >= kvalid) p1[r] = -1e30f; }
;   }
;   PVM(0);
;   float pmax = p0[0];
; #pragma unroll
;   for (int r = 1; r < 16; ++r) pmax = fmaxf(pmax, p0[r]);
;   SBAR();
;   PVM(1);
; #pragma unroll
;   for (int r = 0; r < 16; ++r) pmax = fmaxf(pmax, p1[r]);
;   { auto rr = __builtin_amdgcn_permlane32_swap(__float_as_uint(pmax), __float_as_uint(pmax), false, false);
;     pmax = fmaxf(__uint_as_float(rr[0]), __uint_as_float(rr[1])); }
;   SBAR();
;   PVM(2);
;   if (__builtin_expect(__all(pmax - m_reg <= THR / MLA_SCALE), 1)) { mn = m_reg; alpha = 1.f; }
;   else { mn = fmaxf(m_reg, pmax); alpha = __builtin_amdgcn_exp2f((m_reg - mn) * C); m_reg = mn; }
;   const float mnC = PSHIFT - mn * C;
;   const f32x2 C2 = {C, C}, M2 = {mnC, mnC};
; #pragma unroll
.Lu1_dma_done:
	ds_read_b128 v[114:117], v173 offset:29696
	ds_read_b128 v[198:201], v173 offset:30208
	ds_read_b64 v[118:119], v176 offset:28672
	ds_read_b64 v[202:203], v176 offset:28928
	v_exp_f32_e32 v182, v82
	s_waitcnt lgkmcnt(4)
	v_exp_f32_e32 v214, v83
	v_mfma_scale_f32_32x32x64_f8f6f4 v[96:111], v[204:209], v[120:125], 0, v162, v143 op_sel_hi:[0,0,0] cbsz:2 blgp:2
	v_exp_f32_e32 v160, v160
	v_exp_f32_e32 v161, v161
	v_exp_f32_e32 v158, v158
	v_exp_f32_e32 v159, v159
	v_mfma_scale_f32_32x32x64_f8f6f4 v[80:95], v[216:221], v[120:125], 0, v162, v143 op_sel_hi:[0,0,0] cbsz:2 blgp:2
	ds_read_b128 v[66:69], v173 offset:33792
	ds_read_b128 v[72:75], v173 offset:34304
	ds_read_b64 v[70:71], v176 offset:31744
	ds_read_b64 v[76:77], v176 offset:32000
	s_waitcnt lgkmcnt(4)
	v_mfma_scale_f32_32x32x64_f8f6f4 v[96:111], v[114:119], v[126:131], v[96:111], v162, v143 op_sel_hi:[0,0,0] cbsz:2 blgp:2
	v_exp_f32_e32 v113, v156
	v_exp_f32_e32 v114, v157
	v_exp_f32_e32 v115, v154
	v_exp_f32_e32 v116, v155
	v_exp_f32_e32 v117, v152
	v_mfma_scale_f32_32x32x64_f8f6f4 v[80:95], v[198:203], v[126:131], v[80:95], v162, v143 op_sel_hi:[0,0,0] cbsz:2 blgp:2
	v_exp_f32_e32 v118, v153
	s_waitcnt lgkmcnt(0)
	v_exp_f32_e32 v119, v150
	v_mfma_scale_f32_32x32x64_f8f6f4 v[96:111], v[66:71], v[132:137], v[96:111], v162, v143 op_sel_hi:[0,0,0] cbsz:2 blgp:2
	v_exp_f32_e32 v156, v151
	v_exp_f32_e32 v157, v148
	v_exp_f32_e32 v215, v149
	v_mfma_scale_f32_32x32x64_f8f6f4 v[80:95], v[72:77], v[132:137], v[80:95], v162, v143 op_sel_hi:[0,0,0] cbsz:2 blgp:2
	ds_read_b128 v[72:75], v140 offset:20480
	ds_read_b128 v[76:79], v140 offset:20992
	ds_read_b128 v[148:151], v140 offset:22528
	ds_read_b128 v[152:155], v140 offset:23040
	ds_read_b128 v[198:201], v140 offset:24576
	ds_read_b128 v[202:205], v140 offset:25088
	ds_read_b128 v[206:209], v140 offset:26624
	ds_read_b128 v[210:213], v140 offset:27136
	v_cvt_pk_fp8_f32 v64, v65, v197
	v_cvt_pk_fp8_f32 v68, v160, v161
	v_cvt_pk_fp8_f32 v65, v195, v196
	v_cvt_pk_fp8_f32 v69, v182, v214
	v_cvt_pk_fp8_f32 v66, v193, v194
	v_cvt_pk_fp8_f32 v70, v115, v116
	v_cvt_pk_fp8_f32 v67, v188, v190
	v_cvt_pk_fp8_f32 v71, v119, v156
	v_cvt_pk_fp8_f32 v64, v187, v189 op_sel:[0,0,1]
	v_cvt_pk_fp8_f32 v68, v158, v159 op_sel:[0,0,1]
	v_cvt_pk_fp8_f32 v65, v191, v192 op_sel:[0,0,1]
	v_cvt_pk_fp8_f32 v69, v113, v114 op_sel:[0,0,1]
	v_cvt_pk_fp8_f32 v66, v183, v184 op_sel:[0,0,1]
	v_cvt_pk_fp8_f32 v70, v117, v118 op_sel:[0,0,1]
	v_cvt_pk_fp8_f32 v67, v185, v186 op_sel:[0,0,1]
	v_cvt_pk_fp8_f32 v71, v157, v215 op_sel:[0,0,1]
	s_waitcnt lgkmcnt(0)
	s_nop 0
	v_mfma_scale_f32_32x32x64_f8f6f4 v[0:15], v[64:71], v[72:79], v[0:15], v162, v162 op_sel_hi:[0,0,0]
	v_max_f32_e32 v113, v96, v97
	v_max3_f32 v113, v113, v98, v99
	v_max3_f32 v113, v113, v100, v101
	v_max3_f32 v113, v113, v102, v103
	v_max3_f32 v113, v113, v104, v105
	v_max3_f32 v113, v113, v106, v107
	v_max3_f32 v113, v113, v108, v109
	v_max3_f32 v113, v113, v110, v111
	v_mfma_scale_f32_32x32x64_f8f6f4 v[48:63], v[64:71], v[148:155], v[48:63], v162, v162 op_sel_hi:[0,0,0]
	v_max3_f32 v72, v113, v80, v81
	v_max3_f32 v72, v72, v82, v83
	v_max3_f32 v72, v72, v84, v85
	v_max3_f32 v72, v72, v86, v87
	v_max3_f32 v72, v72, v88, v89
	v_max3_f32 v72, v72, v90, v91
	v_max3_f32 v72, v72, v92, v93
	v_max3_f32 v72, v72, v94, v95
	v_mov_b32_e32 v73, v72
	s_nop 1
	v_permlane32_swap_b32_e32 v72, v73
	v_max_f32_e32 v72, v72, v73
	v_mfma_scale_f32_32x32x64_f8f6f4 v[16:31], v[64:71], v[198:205], v[16:31], v162, v162 op_sel_hi:[0,0,0]
	v_sub_f32_e32 v73, v72, v227
	v_cmp_ge_f32_e32 vcc, s69, v73
	s_cmp_eq_u64 vcc, exec
	s_cselect_b64 s[8:9], -1, 0
	v_mov_b32_e32 v182, 1.0
	v_mfma_scale_f32_32x32x64_f8f6f4 v[32:47], v[64:71], v[206:213], v[32:47], v162, v162 op_sel_hi:[0,0,0]
	v_mfma_scale_f32_16x16x128_f8f6f4 v[240:243], v[232:239], v[64:71], 0, v162, v162 op_sel_hi:[0,0,0]
	ds_read_b128 v[200:203], v173 offset:0
	ds_read_b64 v[204:205], v176 offset:0
	ds_read_b128 v[206:209], v173 offset:512
	ds_read_b64 v[210:211], v176 offset:256
	s_and_b64 vcc, exec, s[8:9]
	s_cbranch_vccnz .Lu1_572
	v_max_f32_e32 v148, v227, v72
	v_sub_f32_e32 v72, v227, v148
	v_mul_f32_e32 v72, 1.0, v72
	v_exp_f32_e32 v182, v72
	v_mov_b32_e32 v227, v148
	v_fmamk_f32 v230, v148, 0xbf800000, v164
	s_and_saveexec_b64 s[16:17], s[6:7]
	ds_write_b32 v178, v182 offset:128
	s_or_b64 exec, exec, s[16:17]
	s_waitcnt lgkmcnt(0)
	v_add_u32_e32 v113, v171, v177
	ds_read_b128 v[72:75], v113 offset:224
	ds_read_b128 v[76:79], v113 offset:192
	ds_read_b128 v[114:117], v113 offset:160
	ds_read_b128 v[150:153], v113 offset:128
	s_waitcnt lgkmcnt(0)
	v_pk_mul_f32 v[12:13], v[12:13], v[72:73]
	v_pk_mul_f32 v[8:9], v[8:9], v[76:77]
	v_pk_mul_f32 v[4:5], v[4:5], v[114:115]
	v_pk_mul_f32 v[14:15], v[14:15], v[74:75]
	v_pk_mul_f32 v[10:11], v[10:11], v[78:79]
	v_pk_mul_f32 v[6:7], v[6:7], v[116:117]
	v_pk_mul_f32 v[2:3], v[2:3], v[152:153]
	v_pk_mul_f32 v[0:1], v[0:1], v[150:151]
	v_pk_mul_f32 v[60:61], v[60:61], v[72:73]
	v_pk_mul_f32 v[56:57], v[56:57], v[76:77]
	v_pk_mul_f32 v[52:53], v[52:53], v[114:115]
	v_pk_mul_f32 v[62:63], v[62:63], v[74:75]
	v_pk_mul_f32 v[58:59], v[58:59], v[78:79]
	v_pk_mul_f32 v[54:55], v[54:55], v[116:117]
	v_pk_mul_f32 v[50:51], v[50:51], v[152:153]
	v_pk_mul_f32 v[48:49], v[48:49], v[150:151]
	v_pk_mul_f32 v[28:29], v[28:29], v[72:73]
	v_pk_mul_f32 v[24:25], v[24:25], v[76:77]
	v_pk_mul_f32 v[20:21], v[20:21], v[114:115]
	v_pk_mul_f32 v[30:31], v[30:31], v[74:75]
	v_pk_mul_f32 v[26:27], v[26:27], v[78:79]
	v_pk_mul_f32 v[22:23], v[22:23], v[116:117]
	v_pk_mul_f32 v[18:19], v[18:19], v[152:153]
	v_pk_mul_f32 v[16:17], v[16:17], v[150:151]
	v_pk_mul_f32 v[44:45], v[44:45], v[72:73]
	v_pk_mul_f32 v[40:41], v[40:41], v[76:77]
	v_pk_mul_f32 v[36:37], v[36:37], v[114:115]
	v_pk_mul_f32 v[46:47], v[46:47], v[74:75]
	v_pk_mul_f32 v[42:43], v[42:43], v[78:79]
	v_pk_mul_f32 v[38:39], v[38:39], v[116:117]
	v_pk_mul_f32 v[34:35], v[34:35], v[152:153]
	v_pk_mul_f32 v[32:33], v[32:33], v[150:151]
; #define SBAR() __builtin_amdgcn_sched_barrier(0)
; #define MFMA8(A, B, C) __builtin_amdgcn_mfma_scale_f32_32x32x64_f8f6f4(A, B, C, 0, 0, 0, 0x7f7f7f7f, 0, 0x7f7f7f7f)
; #define MFMA6(A, B, C) __builtin_amdgcn_mfma_scale_f32_32x32x64_f8f6f4(A, B, C, 2, 2, 0, 0x7f7f7f7f, 0, 0x7f7f7f7f)
; template <bool FUSE>
; DEVINL void qkt(f32x16& p0, f32x16& p1, const char* Ks, const i32x8* q8, int r32, int hi, f32x16& e1) {
;   p0 = f32x16{}; p1 = f32x16{};
;   const char* ka = Ks + hi * 1024 + r32 * 16; const char* kb = Ks + 4096 + hi * 512 + r32 * 8;
;   const char* ra = Ks + 6144 + hi * 1024 + r32 * 16; const char* rb = Ks + 6144 + 2048 + hi * 512 + r32 * 8;
;   u32x4 fa[3][2]; u32x2 fb[3][2];
;     ...
;   QK_LD(0, 0);
; #pragma unroll
;   for (int t = 0; t < 3; ++t) {
;     if (t + 1 < 3) QK_LD(t + 1, (t + 1) % 3);
;     const i32x8 a0 = mk6((int)fa[t][0][0], (int)fa[t][0][1], (int)fa[t][0][2], (int)fa[t][0][3], (int)fb[t][0][0], (int)fb[t][0][1]);
;     const i32x8 a1 = mk6((int)fa[t][1][0], (int)fa[t][1][1], (int)fa[t][1][2], (int)fa[t][1][3], (int)fb[t][1][0], (int)fb[t][1][1]);
;     p0 = MFMA6(a0, q8[t], p0);
;     if (FUSE) {
; #pragma unroll
;       for (int r = 0; r < 3; ++r) { const int rr = t * 6 + r; if (rr < 16) e1[rr] = __builtin_amdgcn_exp2f(e1[rr]); }
;     }
;     p1 = MFMA6(a1, q8[t], p1);
;     if (FUSE) {
; #pragma unroll
;       for (int r = 3; r < 6; ++r) { const int rr = t * 6 + r; if (rr < 16) e1[rr] = __builtin_amdgcn_exp2f(e1[rr]); }
;     }
;     SBAR();
;   }
; DEVINL void pv_psm(f32x16* o, const VFrag& f, const i32x8& pa, f32x16& lsum, const i32x8& ones8,
;                    f32x16& p0, f32x16& p1, float& m_reg, float& mn, float& alpha, int kvalid, int hi) {
;     ...
;   const float mnC = PSHIFT - mn * C;
;   const f32x2 C2 = {C, C}, M2 = {mnC, mnC};
; #pragma unroll
;   for (int r = 0; r < 16; r += 2) { f32x2 v = {p0[r], p0[r + 1]}; v = __builtin_elementwise_fma(v, C2, M2); p0[r] = v[0]; p0[r + 1] = v[1]; }
;   SBAR();
;   PVM(3);
; #pragma unroll
;   for (int r = 0; r < 16; r += 2) { f32x2 v = {p1[r], p1[r + 1]}; v = __builtin_elementwise_fma(v, C2, M2); p1[r] = v[0]; p1[r + 1] = v[1]; }
; #pragma unroll
;   for (int r = 0; r < 8; ++r) p0[r] = __builtin_amdgcn_exp2f(p0[r]);
;   SBAR();
;   lsum = MFMA8(ones8, pa, (f32x16{}));
; #pragma unroll
;   for (int r = 8; r < 16; ++r) p0[r] = __builtin_amdgcn_exp2f(p0[r]);
;   SBAR();
;     ...
; }
.Lu1_572:
	v_pk_fma_f32 v[76:77], v[104:105], s[50:51], v[230:231] op_sel_hi:[1,0,0]
	v_pk_fma_f32 v[68:69], v[96:97], s[50:51], v[230:231] op_sel_hi:[1,0,0]
	v_exp_f32_e32 v198, v77
	v_pk_fma_f32 v[70:71], v[98:99], s[50:51], v[230:231] op_sel_hi:[1,0,0]
	v_pk_fma_f32 v[72:73], v[100:101], s[50:51], v[230:231] op_sel_hi:[1,0,0]
	v_pk_fma_f32 v[74:75], v[102:103], s[50:51], v[230:231] op_sel_hi:[1,0,0]
	v_pk_fma_f32 v[78:79], v[106:107], s[50:51], v[230:231] op_sel_hi:[1,0,0]
	v_pk_fma_f32 v[96:97], v[108:109], s[50:51], v[230:231] op_sel_hi:[1,0,0]
	v_pk_fma_f32 v[98:99], v[110:111], s[50:51], v[230:231] op_sel_hi:[1,0,0]
	v_pk_fma_f32 v[102:103], v[80:81], s[50:51], v[230:231] op_sel_hi:[1,0,0]
	v_pk_fma_f32 v[114:115], v[82:83], s[50:51], v[230:231] op_sel_hi:[1,0,0]
	v_pk_fma_f32 v[116:117], v[84:85], s[50:51], v[230:231] op_sel_hi:[1,0,0]
	v_pk_fma_f32 v[228:229], v[86:87], s[50:51], v[230:231] op_sel_hi:[1,0,0]
	v_pk_fma_f32 v[156:157], v[88:89], s[50:51], v[230:231] op_sel_hi:[1,0,0]
	v_exp_f32_e32 v113, v68
	v_exp_f32_e32 v181, v69
	v_exp_f32_e32 v183, v70
	v_exp_f32_e32 v192, v71
	v_exp_f32_e32 v193, v72
	v_exp_f32_e32 v194, v73
	v_exp_f32_e32 v195, v74
	v_exp_f32_e32 v196, v75
	v_exp_f32_e32 v197, v76
	v_exp_f32_e32 v199, v78
	v_exp_f32_e32 v216, v79
	v_exp_f32_e32 v217, v96
	v_exp_f32_e32 v218, v97
	v_exp_f32_e32 v219, v98
	v_exp_f32_e32 v220, v99
	v_pk_fma_f32 v[158:159], v[90:91], s[50:51], v[230:231] op_sel_hi:[1,0,0]
	v_pk_fma_f32 v[160:161], v[92:93], s[50:51], v[230:231] op_sel_hi:[1,0,0]
	v_pk_fma_f32 v[184:185], v[94:95], s[50:51], v[230:231] op_sel_hi:[1,0,0]
	ds_read_b128 v[98:101], v173 offset:2048
	ds_read_b128 v[104:107], v173 offset:2560
	v_exp_f32_e32 v221, v102
	v_exp_f32_e32 v222, v103
	ds_read_b64 v[102:103], v176 offset:1024
	ds_read_b64 v[108:109], v176 offset:1280
	s_waitcnt lgkmcnt(4)
	v_mfma_scale_f32_32x32x64_f8f6f4 v[66:81], v[200:205], v[120:125], 0, v162, v143 op_sel_hi:[0,0,0] cbsz:2 blgp:2
	v_exp_f32_e32 v223, v114
	v_exp_f32_e32 v224, v115
	v_exp_f32_e32 v225, v116
	v_exp_f32_e32 v226, v117
	v_mfma_scale_f32_32x32x64_f8f6f4 v[82:97], v[206:211], v[120:125], 0, v162, v143 op_sel_hi:[0,0,0] cbsz:2 blgp:2
	ds_read_b128 v[114:117], v173 offset:6144
	ds_read_b128 v[148:151], v173 offset:6656
	ds_read_b64 v[118:119], v176 offset:4096
	ds_read_b64 v[152:153], v176 offset:4352
	s_waitcnt lgkmcnt(4)
	v_mfma_scale_f32_32x32x64_f8f6f4 v[66:81], v[98:103], v[126:131], v[66:81], v162, v143 op_sel_hi:[0,0,0] cbsz:2 blgp:2
	v_exp_f32_e32 v100, v228
	v_exp_f32_e32 v101, v229
	v_exp_f32_e32 v110, v156
	v_exp_f32_e32 v111, v157
	v_exp_f32_e32 v156, v158
	v_exp_f32_e32 v157, v159
	v_mfma_scale_f32_32x32x64_f8f6f4 v[82:97], v[104:109], v[126:131], v[82:97], v162, v143 op_sel_hi:[0,0,0] cbsz:2 blgp:2
	s_waitcnt lgkmcnt(0)
	v_exp_f32_e32 v106, v160
	v_mfma_scale_f32_32x32x64_f8f6f4 v[66:81], v[114:119], v[132:137], v[66:81], v162, v143 op_sel_hi:[0,0,0] cbsz:2 blgp:2
	v_exp_f32_e32 v107, v161
	v_exp_f32_e32 v108, v184
	v_exp_f32_e32 v109, v185
	v_mfma_scale_f32_32x32x64_f8f6f4 v[82:97], v[148:153], v[132:137], v[82:97], v162, v143 op_sel_hi:[0,0,0] cbsz:2 blgp:2
	ds_read_b128 v[148:151], v140 offset:28672
	ds_read_b128 v[152:155], v140 offset:29184
	ds_read_b128 v[184:187], v140 offset:30720
	ds_read_b128 v[188:191], v140 offset:31232
	ds_read_b128 v[200:203], v140 offset:32768
	ds_read_b128 v[204:207], v140 offset:33280
	ds_read_b128 v[208:211], v140 offset:34816
	ds_read_b128 v[212:215], v140 offset:35328
	v_cvt_pk_fp8_f32 v103, v225, v226
	v_cvt_pk_fp8_f32 v98, v113, v181
	v_cvt_pk_fp8_f32 v102, v221, v222
	v_cvt_pk_fp8_f32 v99, v193, v194
	v_cvt_pk_fp8_f32 v103, v100, v101 op_sel:[0,0,1]
	v_cvt_pk_fp8_f32 v100, v197, v198
	v_cvt_pk_fp8_f32 v104, v110, v111
	v_cvt_pk_fp8_f32 v101, v217, v218
	v_cvt_pk_fp8_f32 v105, v106, v107
	v_cvt_pk_fp8_f32 v98, v183, v192 op_sel:[0,0,1]
	v_cvt_pk_fp8_f32 v102, v223, v224 op_sel:[0,0,1]
	v_cvt_pk_fp8_f32 v99, v195, v196 op_sel:[0,0,1]
	v_cvt_pk_fp8_f32 v100, v199, v216 op_sel:[0,0,1]
	v_cvt_pk_fp8_f32 v104, v156, v157 op_sel:[0,0,1]
	v_cvt_pk_fp8_f32 v101, v219, v220 op_sel:[0,0,1]
	v_cvt_pk_fp8_f32 v105, v108, v109 op_sel:[0,0,1]
	s_waitcnt lgkmcnt(0)
	s_nop 0
	v_mfma_scale_f32_32x32x64_f8f6f4 v[0:15], v[98:105], v[148:155], v[0:15], v162, v162 op_sel_hi:[0,0,0]
	s_cmpk_gt_u32 s53, 0x101
	s_cbranch_scc1 .Lmask_last
; #define SBAR() __builtin_amdgcn_sched_barrier(0)
; #define PVM(db) do { const i32x8 b = {(int)f.v[db][0][0], (int)f.v[db][0][1], (int)f.v[db][0][2], (int)f.v[db][0][3], (int)f.v[db][1][0], (int)f.v[db][1][1], (int)f.v[db][1][2], (int)f.v[db][1][3]}; \
;     o[db] = MFMA8(pa, b, o[db]); } while (0)
; DEVINL void pv_psm(f32x16* o, const VFrag& f, const i32x8& pa, f32x16& lsum, const i32x8& ones8,
;                    f32x16& p0, f32x16& p1, float& m_reg, float& mn, float& alpha, int kvalid, int hi) {
;     ...
;   float pmax = p0[0];
; #pragma unroll
;   for (int r = 1; r < 16; ++r) pmax = fmaxf(pmax, p0[r]);
;   SBAR();
;   PVM(1);
; #pragma unroll
;   for (int r = 0; r < 16; ++r) pmax = fmaxf(pmax, p1[r]);
;   { auto rr = __builtin_amdgcn_permlane32_swap(__float_as_uint(pmax), __float_as_uint(pmax), false, false);
;     pmax = fmaxf(__uint_as_float(rr[0]), __uint_as_float(rr[1])); }
;   SBAR();
;   PVM(2);
;   if (__builtin_expect(__all(pmax - m_reg <= THR / MLA_SCALE), 1)) { mn = m_reg; alpha = 1.f; }
;   else { mn = fmaxf(m_reg, pmax); alpha = __builtin_amdgcn_exp2f((m_reg - mn) * C); m_reg = mn; }
.Lmask_ret:
	v_max_f32_e32 v241, v66, v67
	v_max3_f32 v241, v241, v68, v69
	v_max3_f32 v241, v241, v70, v71
	v_max3_f32 v241, v241, v72, v73
	v_max3_f32 v241, v241, v74, v75
	v_max3_f32 v241, v241, v76, v77
	v_max3_f32 v241, v241, v78, v79
	v_max3_f32 v241, v241, v80, v81
	v_mfma_scale_f32_32x32x64_f8f6f4 v[48:63], v[98:105], v[184:191], v[48:63], v162, v162 op_sel_hi:[0,0,0]
	v_max3_f32 v241, v241, v82, v83
	v_max3_f32 v241, v241, v84, v85
	v_max3_f32 v241, v241, v86, v87
	v_max3_f32 v241, v241, v88, v89
	v_max3_f32 v241, v241, v90, v91
	v_max3_f32 v241, v241, v92, v93
	v_max3_f32 v241, v241, v94, v95
	v_max3_f32 v241, v241, v96, v97
	v_mov_b32_e32 v242, v241
	s_nop 1
	v_permlane32_swap_b32_e32 v241, v242
	v_max_f32_e32 v241, v241, v242
	v_mfma_scale_f32_32x32x64_f8f6f4 v[16:31], v[98:105], v[200:207], v[16:31], v162, v162 op_sel_hi:[0,0,0]
	v_sub_f32_e32 v242, v241, v227
	v_cmp_ge_f32_e32 vcc, s69, v242
	s_cmp_eq_u64 vcc, exec
	s_cselect_b64 s[8:9], -1, 0
	v_mov_b32_e32 v198, 1.0
	v_mfma_scale_f32_32x32x64_f8f6f4 v[32:47], v[98:105], v[208:215], v[32:47], v162, v162 op_sel_hi:[0,0,0]
	s_waitcnt vmcnt(0)
	s_waitcnt vmcnt(0)
	s_barrier
	s_and_b64 vcc, exec, s[8:9]
	s_cbranch_vccnz .Lu1_576
	v_max_f32_e32 v241, v227, v241
	v_sub_f32_e32 v243, v227, v241
	v_mul_f32_e32 v243, 1.0, v243
	v_exp_f32_e32 v198, v243
	v_mov_b32_e32 v227, v241
	v_fmamk_f32 v230, v241, 0xbf800000, v164
	s_and_saveexec_b64 s[16:17], s[6:7]
	ds_write_b32 v178, v198 offset:128
	s_or_b64 exec, exec, s[16:17]
	s_waitcnt lgkmcnt(0)
	v_add_u32_e32 v242, v171, v177
	ds_read_b128 v[244:247], v242 offset:224
	ds_read_b128 v[116:119], v242 offset:192
	ds_read_b128 v[148:151], v242 offset:160
	ds_read_b128 v[152:155], v242 offset:128
	s_waitcnt lgkmcnt(3)
	v_pk_mul_f32 v[12:13], v[12:13], v[244:245]
	s_waitcnt lgkmcnt(2)
	v_pk_mul_f32 v[8:9], v[8:9], v[116:117]
	s_waitcnt lgkmcnt(1)
	v_pk_mul_f32 v[4:5], v[4:5], v[148:149]
	v_pk_mul_f32 v[14:15], v[14:15], v[246:247]
	v_pk_mul_f32 v[10:11], v[10:11], v[118:119]
	v_pk_mul_f32 v[6:7], v[6:7], v[150:151]
	s_waitcnt lgkmcnt(0)
	v_pk_mul_f32 v[2:3], v[2:3], v[154:155]
	v_pk_mul_f32 v[0:1], v[0:1], v[152:153]
	v_pk_mul_f32 v[60:61], v[60:61], v[244:245]
	v_pk_mul_f32 v[56:57], v[56:57], v[116:117]
	v_pk_mul_f32 v[52:53], v[52:53], v[148:149]
	v_pk_mul_f32 v[62:63], v[62:63], v[246:247]
	v_pk_mul_f32 v[58:59], v[58:59], v[118:119]
	v_pk_mul_f32 v[54:55], v[54:55], v[150:151]
	v_pk_mul_f32 v[50:51], v[50:51], v[154:155]
	v_pk_mul_f32 v[48:49], v[48:49], v[152:153]
	v_pk_mul_f32 v[28:29], v[28:29], v[244:245]
	v_pk_mul_f32 v[24:25], v[24:25], v[116:117]
	v_pk_mul_f32 v[20:21], v[20:21], v[148:149]
	v_pk_mul_f32 v[30:31], v[30:31], v[246:247]
	v_pk_mul_f32 v[26:27], v[26:27], v[118:119]
	v_pk_mul_f32 v[22:23], v[22:23], v[150:151]
	v_pk_mul_f32 v[18:19], v[18:19], v[154:155]
	v_pk_mul_f32 v[16:17], v[16:17], v[152:153]
	v_pk_mul_f32 v[44:45], v[44:45], v[244:245]
	v_pk_mul_f32 v[40:41], v[40:41], v[116:117]
	v_pk_mul_f32 v[36:37], v[36:37], v[148:149]
	v_pk_mul_f32 v[46:47], v[46:47], v[246:247]
	v_pk_mul_f32 v[42:43], v[42:43], v[118:119]
	v_pk_mul_f32 v[38:39], v[38:39], v[150:151]
	v_pk_mul_f32 v[34:35], v[34:35], v[154:155]
	v_pk_mul_f32 v[32:33], v[32:33], v[152:153]
